# scan phase split into stepper waves 0-3 (hand-written step code) and prepper waves 4-7 (prep for next chunk)
# speedup vs baseline: 1.0289x; 1.0289x over previous
.LBB0_321:
	s_cmp_lt_u32 s6, 4
	s_cbranch_scc1 .Lst_entry
	s_and_b32 s21, s6, 3
	s_mov_b32 s30, 0
.Lpp_seg:
	s_mov_b32 s6, s21
	s_mov_b32 s10, 0
	s_mov_b32 s11, s52
	s_mov_b32 s16, s53
	s_mov_b64 s[24:25], s[54:55]
	s_mov_b32 s19, s78
	s_cmp_eq_u32 s30, 0
	s_cselect_b64 s[0:1], -1, 0
	s_movk_i32 s20, 0x200
	s_cselect_b32 s20, 0x100, s20
	s_cmp_lt_i32 s19, s20
	s_cselect_b64 s[2:3], -1, 0
	s_and_b64 s[4:5], s[0:1], exec
	s_cselect_b32 s31, 0x100, 16
	s_andn2_b64 vcc, exec, s[2:3]
	s_cbranch_vccnz .LBB0_339
	s_ashr_i32 s26, s6, 2
	s_add_i32 s65, s10, 0
	s_and_b32 s6, s6, 3
	s_mul_i32 s2, s26, 0x10700
	s_add_i32 s34, s65, s2
	s_lshl_b32 s2, s6, 12
	s_ashr_i32 s4, s14, 1
	s_lshl_b32 s35, s6, 4
	s_add_i32 s27, s34, s2
	s_add_u32 s2, s24, 0x2800000
	s_addc_u32 s3, s25, 0
	s_add_u32 s44, s24, 0x100000
	s_mul_i32 s5, s6, 0xfffff004
	s_addc_u32 s45, s25, 0
	s_add_i32 s28, s27, s5
	v_mov_b32_e32 v0, s11
	s_and_b64 s[10:11], s[0:1], exec
	s_cselect_b32 s46, s61, 0x100
	s_ashr_i32 s5, s4, 31
	v_mov_b32_e32 v1, s16
	s_and_b32 s47, s14, -2
	s_lshl_b64 s[16:17], s[4:5], 10
	v_and_b32_e32 v68, 15, v69
	v_ashrrev_i32_e32 v73, 4, v69
	v_ashrrev_i32_e32 v2, 2, v69
	v_lshlrev_b32_e32 v5, 4, v69
	s_movk_i32 s4, 0xffef
	s_cmp_eq_u32 s6, 0
	v_lshl_add_u32 v130, v73, 2, s35
	v_and_b32_e32 v2, -2, v2
	v_mul_u32_u24_e32 v3, 0x184, v68
	v_add_u32_e32 v134, s34, v5
	v_bitop3_b32 v6, v69, s4, 15 bitop3:0x6c
	v_cmp_gt_i32_e32 vcc, 16, v69
	s_cselect_b64 s[4:5], -1, 0
	v_add_u32_e32 v131, s35, v2
	v_lshlrev_b32_e32 v2, 2, v130
	v_lshlrev_b32_e32 v3, 2, v3
	v_lshl_add_u32 v135, s6, 2, v134
	s_and_b64 s[4:5], vcc, s[4:5]
	s_lshl_b32 s6, s6, 6
	v_and_b32_e32 v4, 7, v69
	v_add3_u32 v133, s34, v3, v2
	v_add3_u32 v138, s34, v2, v3
	v_and_b32_e32 v2, 0x3ffffff8, v69
	s_add_u32 s10, s24, s6
	v_add_u32_e32 v137, s46, v6
	v_lshlrev_b32_e32 v6, 2, v4
	v_lshlrev_b32_e32 v2, 2, v2
	s_addc_u32 s11, s25, 0
	v_lshlrev_b32_e32 v148, 2, v68
	v_add3_u32 v139, s27, v6, v2
	v_lshl_add_u64 v[2:3], s[10:11], 0, v[148:149]
	s_mov_b64 s[10:11], 0x12400000
	v_lshl_add_u64 v[76:77], v[2:3], 0, s[10:11]
	v_lshlrev_b32_e32 v2, 8, v69
	v_lshlrev_b32_e32 v74, 3, v73
	v_and_b32_e32 v2, 0x100, v2
	v_and_b32_e32 v3, 0xe0, v5
	v_lshlrev_b32_e32 v70, 6, v131
	v_ashrrev_i32_e32 v75, 31, v74
	v_add3_u32 v6, s27, v2, v3
	v_add_u32_e32 v2, 64, v69
	v_ashrrev_i32_e32 v71, 31, v70
	v_ashrrev_i32_e32 v141, 4, v2
	v_lshl_add_u64 v[2:3], v[74:75], 1, s[24:25]
	s_mov_b64 s[24:25], 0x1480000
	v_lshl_add_u64 v[78:79], v[2:3], 0, s[24:25]
	s_mov_b64 s[24:25], 0x14c0000
	v_lshl_add_u64 v[0:1], v[70:71], 2, v[0:1]
	v_lshlrev_b32_e32 v148, 5, v4
	v_lshl_add_u64 v[80:81], v[2:3], 0, s[24:25]
	v_lshl_add_u64 v[0:1], v[0:1], 0, v[148:149]
	s_mov_b64 s[24:25], 0x9000000
	v_lshl_add_u64 v[82:83], v[0:1], 0, s[24:25]
	v_and_b32_e32 v1, 64, v188
	v_xor_b32_e32 v0, 16, v188
	v_add_u32_e32 v1, 64, v1
	v_cmp_lt_i32_e32 vcc, v0, v1
	s_add_i32 s48, s31, -1
	v_add_u32_e32 v140, s28, v5
	v_cndmask_b32_e32 v0, v188, v0, vcc
	v_lshlrev_b32_e32 v142, 2, v0
	v_xor_b32_e32 v0, 32, v188
	v_cmp_lt_i32_e32 vcc, v0, v1
	s_cmp_eq_u32 s26, 1
	v_lshlrev_b32_e32 v5, 9, v73
	v_lshlrev_b32_e32 v7, 9, v141
	v_cndmask_b32_e32 v0, v188, v0, vcc
	s_mov_b32 s33, 1
	v_lshlrev_b32_e32 v72, 3, v4
	v_xad_u32 v132, v68, -1, s46
	v_cmp_gt_u32_e64 s[38:39], 16, v69
	v_or_b32_e32 v136, 16, v68
	s_cselect_b64 s[10:11], -1, 0
	s_add_i32 s49, s65, 0x23e78
	s_add_i32 s56, s65, 0x23e90
	s_add_i32 s57, s65, 0x23eb8
	s_add_i32 s62, s65, 0x23ec0
	s_add_i32 s64, s65, 0x23ec8
	s_add_i32 s65, s65, 0x23e10
	v_lshlrev_b32_e32 v143, 2, v0
	v_sub_u32_e32 v144, 0, v141
	v_sub_u32_e32 v145, 0, v73
	v_not_b32_e32 v146, v69
	s_lshl_b64 s[24:25], s[16:17], 2
	v_add_u32_e32 v147, v6, v5
	v_add_u32_e32 v164, v6, v7
	s_branch .LBB0_324

.LBB0_329:
	s_or_b64 exec, exec, s[16:17]
	v_cndmask_b32_e64 v36, v137, v136, s[40:41]
	s_lshl_b32 s28, s72, 6
	v_add_u32_e32 v38, s26, v36
	v_mov_b64_e32 v[36:37], s[2:3]
	v_mad_i64_i32 v[86:87], s[16:17], v38, s63, v[36:37]
	s_lshl_b32 s28, s28, 1
	s_mov_b32 s29, s7
	v_lshl_add_u64 v[36:37], v[86:87], 0, s[28:29]
	v_lshl_add_u64 v[36:37], v[74:75], 1, v[36:37]
	v_add_co_u32_e32 v48, vcc, 0x1000, v36
	v_lshl_add_u64 v[88:89], v[86:87], 0, s[6:7]
	s_nop 0
	v_addc_co_u32_e32 v49, vcc, 0, v37, vcc
	v_add_co_u32_e32 v88, vcc, 0x1000, v88
	v_lshl_add_u64 v[86:87], v[84:85], 1, v[86:87]
	s_nop 0
	v_addc_co_u32_e32 v89, vcc, 0, v89, vcc
	v_add_co_u32_e32 v92, vcc, 0x1000, v86
	v_lshl_add_u64 v[38:39], v[36:37], 0, s[66:67]
	v_lshl_add_u64 v[36:37], v[36:37], 0, s[36:37]
	v_addc_co_u32_e32 v93, vcc, 0, v87, vcc
	s_waitcnt lgkmcnt(6)
	global_load_dwordx4 v[208:211], v[48:49], off offset:2304
	global_load_dwordx4 v[204:207], v[36:37], off offset:64
	s_nop 0
	global_load_dwordx4 v[212:215], v[38:39], off offset:64
	s_nop 0
	global_load_dwordx4 v[200:203], v[48:49], off offset:2048
	s_nop 0
	global_load_dword v222, v[88:89], off offset:2816
	s_nop 0
	global_load_dwordx2 v[220:221], v[92:93], off
	s_nop 0
	global_load_dwordx2 v[218:219], v[86:87], off offset:2048
	global_load_dwordx2 v[216:217], v[86:87], off
	s_lshl_b32 s16, s70, 3
	s_add_u32 s16, s44, s16
	s_addc_u32 s17, s45, 0
	s_lshl_b32 s29, s72, 2
	s_add_u32 s42, s16, s29
	s_waitcnt lgkmcnt(0)
	s_barrier
	s_addc_u32 s43, s17, 0
	s_lshl_b32 s16, s27, 2
	s_mov_b32 s17, s7
	s_ashr_i32 s27, s26, 31
	v_lshl_add_u64 v[86:87], v[76:77], 0, s[16:17]
	s_lshl_b64 s[16:17], s[26:27], 12
	s_mov_b32 s73, 0
	v_lshl_add_u64 v[86:87], v[86:87], 0, s[16:17]
	s_mov_b32 s27, s46
	s_mov_b32 s29, 0
	s_mov_b32 s74, 0
.Lpp_chunk:
	s_and_saveexec_b64 s[16:17], s[4:5]
	s_cbranch_execz .Lpp_cs_done
	v_lshl_add_u32 v91, s33, 9, v134
	ds_read_b128 v[96:99], v91 offset:49920
	v_add_u32_e32 v91, s73, v69
	v_add_u32_e32 v100, s27, v146
	v_cndmask_b32_e64 v91, v100, v91, s[40:41]
	s_waitcnt lgkmcnt(0)
	v_mov_b32_e32 v100, v97
	v_mov_b32_e32 v101, v98
	v_mov_b32_e32 v97, v99
	v_pk_add_f32 v[96:97], v[100:101], v[96:97]
	s_nop 0
	v_add_f32_e32 v98, v96, v97
	v_add_u32_e32 v96, s26, v91
	v_ashrrev_i32_e32 v97, 31, v96
	v_lshlrev_b64 v[96:97], 7, v[96:97]
	v_lshl_add_u64 v[96:97], s[42:43], 0, v[96:97]
	global_store_dword v[96:97], v98, off
.Lpp_cs_done:
	s_or_b64 exec, exec, s[16:17]
	s_xor_b32 s33, s33, 1
	s_add_i32 s75, s74, 1
	s_cmp_ge_u32 s75, s31
	s_cbranch_scc1 .Lpp_nomore
	s_waitcnt vmcnt(0)
	v_mov_b32_e32 v36, v200
	v_mov_b32_e32 v37, v201
	v_mov_b32_e32 v38, v202
	v_mov_b32_e32 v39, v203
	v_mov_b32_e32 v40, v204
	v_mov_b32_e32 v41, v205
	v_mov_b32_e32 v42, v206
	v_mov_b32_e32 v43, v207
	v_mov_b32_e32 v86, v208
	v_mov_b32_e32 v87, v209
	v_mov_b32_e32 v88, v210
	v_mov_b32_e32 v89, v211
	v_mov_b32_e32 v90, v212
	v_mov_b32_e32 v91, v213
	v_mov_b32_e32 v92, v214
	v_mov_b32_e32 v93, v215
	v_mov_b32_e32 v94, v216
	v_mov_b32_e32 v95, v217
	v_mov_b32_e32 v50, v218
	v_mov_b32_e32 v51, v219
	v_mov_b32_e32 v96, v220
	v_mov_b32_e32 v97, v221
	v_mov_b32_e32 v48, v222
	s_add_i32 s16, s74, 2
	s_cmp_ge_u32 s16, s31
	s_cbranch_scc1 .Lpp_nopf
	v_lshl_or_b32 v110, s16, 4, v68
	v_xad_u32 v111, v110, -1, s46
	v_cndmask_b32_e64 v110, v111, v110, s[40:41]
	v_add_u32_e32 v112, s26, v110
	v_mov_b64_e32 v[110:111], s[2:3]
	v_mad_i64_i32 v[110:111], s[16:17], v112, s63, v[110:111]
	v_lshl_add_u64 v[114:115], v[84:85], 1, v[110:111]
	v_lshl_add_u64 v[116:117], v[110:111], 0, s[6:7]
	v_lshl_add_u64 v[110:111], v[110:111], 0, s[28:29]
	v_lshl_add_u64 v[118:119], v[74:75], 1, v[110:111]
	v_lshl_add_u64 v[120:121], v[118:119], 0, s[36:37]
	v_lshl_add_u64 v[122:123], v[118:119], 0, s[66:67]
	v_lshl_add_u64 v[124:125], v[114:115], 0, s[92:93]
	v_lshl_add_u64 v[126:127], v[116:117], 0, s[92:93]
	v_lshl_add_u64 v[128:129], v[118:119], 0, s[92:93]
	global_load_dwordx2 v[216:217], v[114:115], off
	global_load_dwordx2 v[218:219], v[114:115], off offset:2048
	global_load_dwordx2 v[220:221], v[124:125], off
	global_load_dword v222, v[126:127], off offset:2816
	global_load_dwordx4 v[200:203], v[128:129], off offset:2048
	global_load_dwordx4 v[208:211], v[128:129], off offset:2304
	global_load_dwordx4 v[204:207], v[120:121], off offset:64
	global_load_dwordx4 v[212:215], v[122:123], off offset:64
.Lpp_nopf:
	s_mul_i32 s16, s33, 0x6100
	v_mfma_f32_16x16x32_bf16 v[36:39], v[0:3], v[36:39], 0
	v_mfma_f32_16x16x32_bf16 v[44:47], v[4:7], v[40:43], v[36:39]
	v_mfma_f32_16x16x32_bf16 v[36:39], v[8:11], v[86:89], 0
	v_lshlrev_b32_e32 v88, 16, v50
	s_nop 5
	v_add_f32_e32 v44, v16, v44
	v_add_f32_e32 v45, v17, v45
	v_mfma_f32_16x16x32_bf16 v[40:43], v[12:15], v[90:93], v[36:39]
	v_mul_f32_e32 v44, 0xbfb8aa3b, v44
	v_mul_f32_e32 v45, 0xbfb8aa3b, v45
	v_exp_f32_e32 v44, v44
	v_exp_f32_e32 v45, v45
	v_add_f32_e32 v46, v18, v46
	s_nop 2
	v_add_f32_e32 v42, v22, v42
	v_mul_f32_e32 v42, 0xbfb8aa3b, v42
	v_exp_f32_e32 v42, v42
	v_add_f32_e32 v44, 1.0, v44
	v_add_f32_e32 v45, 1.0, v45
	v_rcp_f32_e32 v44, v44
	v_add_f32_e32 v42, 1.0, v42
	v_rcp_f32_e32 v92, v42
	v_add_f32_e32 v42, v19, v47
	v_mul_f32_e32 v42, 0xbfb8aa3b, v42
	v_exp_f32_e32 v42, v42
	v_rcp_f32_e32 v45, v45
	v_add_f32_e32 v40, v20, v40
	v_add_f32_e32 v41, v21, v41
	v_add_f32_e32 v42, 1.0, v42
	v_rcp_f32_e32 v42, v42
	v_mul_f32_e32 v46, 0xbfb8aa3b, v46
	v_mul_f32_e32 v40, 0xbfb8aa3b, v40
	v_mul_f32_e32 v41, 0xbfb8aa3b, v41
	v_mul_f32_e32 v42, 0xbf1b4598, v42
	v_mul_f32_e32 v42, 0x3fb8aa3b, v42
	v_exp_f32_e32 v47, v42
	v_add_f32_e32 v42, v23, v43
	v_exp_f32_e32 v46, v46
	v_mul_f32_e32 v42, 0xbfb8aa3b, v42
	v_mul_f32_e32 v44, 0xbf1b4598, v44
	v_exp_f32_e32 v40, v40
	v_mul_f32_e32 v45, 0xbf1b4598, v45
	v_exp_f32_e32 v41, v41
	v_exp_f32_e32 v42, v42
	v_mul_f32_e32 v44, 0x3fb8aa3b, v44
	v_mul_f32_e32 v45, 0x3fb8aa3b, v45
	v_exp_f32_e32 v44, v44
	v_exp_f32_e32 v45, v45
	v_add_f32_e32 v46, 1.0, v46
	v_add_f32_e32 v40, 1.0, v40
	v_add_f32_e32 v41, 1.0, v41
	v_rcp_f32_e32 v46, v46
	v_add_f32_e32 v42, 1.0, v42
	v_rcp_f32_e32 v40, v40
	v_rcp_f32_e32 v41, v41
	v_rcp_f32_e32 v93, v42
	v_mov_b32_e32 v42, 1.0
	v_mov_b32_e32 v43, 1.0
	v_mul_f32_e32 v46, 0xbf1b4598, v46
	v_mov_b32_dpp v42, v44 row_shr:1 row_mask:0xf bank_mask:0xf
	v_mov_b32_dpp v43, v45 row_shr:1 row_mask:0xf bank_mask:0xf
	v_pk_mul_f32 v[42:43], v[44:45], v[42:43]
	v_mov_b32_e32 v44, 1.0
	v_mov_b32_e32 v45, 1.0
	v_mul_f32_e32 v46, 0x3fb8aa3b, v46
	v_mov_b32_dpp v44, v42 row_shr:2 row_mask:0xf bank_mask:0xf
	v_mov_b32_dpp v45, v43 row_shr:2 row_mask:0xf bank_mask:0xf
	v_pk_mul_f32 v[42:43], v[42:43], v[44:45]
	v_mov_b32_e32 v44, 1.0
	v_mov_b32_e32 v45, 1.0
	v_pk_add_f32 v[104:105], v[92:93], -1.0 op_sel_hi:[1,0]
	v_pk_add_f32 v[106:107], v[40:41], -1.0 op_sel_hi:[1,0]
	v_and_b32_e32 v89, 0xffff0000, v50
	v_lshlrev_b32_e32 v90, 16, v51
	v_and_b32_e32 v91, 0xffff0000, v51
	v_exp_f32_e32 v46, v46
	v_mov_b32_dpp v44, v42 row_shr:4 row_mask:0xf bank_mask:0xf
	v_mov_b32_dpp v45, v43 row_shr:4 row_mask:0xf bank_mask:0xf
	v_pk_fma_f32 v[106:107], v[28:29], v[106:107], 1.0 op_sel_hi:[1,1,0]
	v_pk_fma_f32 v[104:105], v[30:31], v[104:105], 1.0 op_sel_hi:[1,1,0]
	v_lshlrev_b32_e32 v50, 16, v94
	v_and_b32_e32 v51, 0xffff0000, v94
	v_lshlrev_b32_e32 v86, 16, v95
	v_and_b32_e32 v87, 0xffff0000, v95
	v_pk_mul_f32 v[42:43], v[42:43], v[44:45]
	v_mov_b32_e32 v44, 1.0
	v_mov_b32_e32 v45, 1.0
	v_pk_mul_f32 v[102:103], v[24:25], v[88:89]
	v_pk_mul_f32 v[104:105], v[104:105], v[90:91]
	v_pk_mul_f32 v[106:107], v[106:107], v[88:89]
	v_mov_b32_dpp v44, v42 row_shr:8 row_mask:0xf bank_mask:0xf
	v_mov_b32_dpp v45, v43 row_shr:8 row_mask:0xf bank_mask:0xf
	v_pk_mul_f32 v[108:109], v[102:103], v[40:41]
	v_pk_mul_f32 v[40:41], v[106:107], v[50:51]
	v_pk_mul_f32 v[88:89], v[104:105], v[86:87]
	v_pk_mul_f32 v[42:43], v[42:43], v[44:45]
	v_mov_b32_e32 v44, 1.0
	v_mov_b32_e32 v45, 1.0
	v_pk_mul_f32 v[88:89], v[34:35], v[88:89]
	v_pk_mul_f32 v[40:41], v[32:33], v[40:41]
	v_mov_b32_dpp v44, v46 row_shr:1 row_mask:0xf bank_mask:0xf
	v_mov_b32_dpp v45, v47 row_shr:1 row_mask:0xf bank_mask:0xf
	v_add_f32_e32 v40, v40, v41
	v_add_f32_e32 v41, v88, v89
	v_pk_mul_f32 v[44:45], v[46:47], v[44:45]
	v_mov_b32_e32 v46, 1.0
	v_mov_b32_e32 v47, 1.0
	v_add_f32_e32 v40, v40, v41
	v_mov_b32_dpp v46, v44 row_shr:2 row_mask:0xf bank_mask:0xf
	v_mov_b32_dpp v47, v45 row_shr:2 row_mask:0xf bank_mask:0xf
	ds_bpermute_b32 v41, v142, v40
	v_pk_mul_f32 v[44:45], v[44:45], v[46:47]
	v_mov_b32_e32 v46, 1.0
	v_mov_b32_e32 v47, 1.0
	v_lshlrev_b32_e32 v36, 16, v96
	v_mov_b32_dpp v46, v44 row_shr:4 row_mask:0xf bank_mask:0xf
	v_mov_b32_dpp v47, v45 row_shr:4 row_mask:0xf bank_mask:0xf
	v_pk_mul_f32 v[44:45], v[44:45], v[46:47]
	v_mov_b32_e32 v46, 1.0
	v_mov_b32_e32 v47, 1.0
	s_waitcnt lgkmcnt(0)
	v_add_f32_e32 v40, v40, v41
	v_mov_b32_dpp v46, v44 row_shr:8 row_mask:0xf bank_mask:0xf
	v_mov_b32_dpp v47, v45 row_shr:8 row_mask:0xf bank_mask:0xf
	v_pk_mul_f32 v[44:45], v[44:45], v[46:47]
	v_and_b32_e32 v37, 0xffff0000, v96
	v_lshlrev_b32_e32 v38, 16, v97
	v_and_b32_e32 v39, 0xffff0000, v97
	v_rcp_f32_e32 v96, v42
	v_rcp_f32_e32 v97, v43
	v_rcp_f32_e32 v98, v44
	v_rcp_f32_e32 v99, v45
	ds_bpermute_b32 v41, v143, v40
	v_mov_b32_e32 v94, 1.0
	v_mov_b32_e32 v95, 1.0
	v_mov_b32_e32 v46, 1.0
	v_mov_b32_e32 v47, 1.0
	v_mov_b32_dpp v94, v42 row_shr:1 row_mask:0xf bank_mask:0xf
	v_mov_b32_dpp v95, v43 row_shr:1 row_mask:0xf bank_mask:0xf
	v_mov_b32_dpp v46, v44 row_shr:1 row_mask:0xf bank_mask:0xf
	v_mov_b32_dpp v47, v45 row_shr:1 row_mask:0xf bank_mask:0xf
	v_pk_mul_f32 v[100:101], v[26:27], v[90:91]
	v_pk_mul_f32 v[88:89], v[102:103], v[94:95]
	v_pk_mul_f32 v[92:93], v[100:101], v[92:93]
	v_pk_mul_f32 v[46:47], v[100:101], v[46:47]
	v_pk_mul_f32 v[88:89], v[48:49], v[88:89] op_sel_hi:[0,1] neg_lo:[1,0] neg_hi:[1,0]
	v_pk_mul_f32 v[90:91], v[48:49], v[46:47] op_sel_hi:[0,1] neg_lo:[1,0] neg_hi:[1,0]
	v_pk_mul_f32 v[48:49], v[92:93], v[98:99]
	v_pk_mul_f32 v[46:47], v[108:109], v[96:97]
	v_pk_mul_f32 v[92:93], v[106:107], v[96:97]
	v_pk_mul_f32 v[96:97], v[42:43], v[50:51]
	v_add_u32_e32 v50, s16, v133
	v_pk_mul_f32 v[94:95], v[104:105], v[98:99]
	v_pk_mul_f32 v[98:99], v[44:45], v[86:87]
	ds_write_b128 v50, v[42:45]
	ds_write_b128 v50, v[88:91] offset:256
	ds_write_b128 v50, v[46:49] offset:512
	ds_write_b128 v50, v[92:95] offset:768
	ds_write_b128 v50, v[96:99] offset:1024
	ds_write_b128 v50, v[36:39] offset:1280
	s_and_saveexec_b64 s[16:17], s[38:39]
	s_cbranch_execz .Lpp_math_end
	v_lshl_add_u32 v36, s33, 9, v135
	s_waitcnt lgkmcnt(6)
	v_add_f32_e32 v37, v40, v41
	ds_write_b32 v36, v37 offset:49920

.Lpp_nomore:
	s_waitcnt lgkmcnt(0)
	s_barrier
	s_add_i32 s73, s73, 16
	s_add_i32 s27, s27, -16
	s_mov_b32 s74, s75
	s_cmp_lt_u32 s74, s31
	s_cbranch_scc1 .Lpp_chunk

.LBB0_339:
	s_add_i32 s30, s30, 1
	s_cmp_lt_u32 s30, 2
	s_cbranch_scc1 .Lpp_seg
	s_branch .LBB0_341
.Lst_entry:
	s_mov_b32 s20, s52
	s_mov_b32 s21, s53
	s_add_i32 s2, s10, 0x23e10
	v_mov_b32_e32 v0, s2
	ds_read2_b32 v[0:1], v0 offset1:1
	v_mbcnt_lo_u32_b32 v142, -1, 0
	v_mbcnt_hi_u32_b32 v142, -1, v142
	v_mov_b32_e32 v185, 0
	v_mov_b32_e32 v187, 0
	s_waitcnt lgkmcnt(0)
	v_readfirstlane_b32 s56, v0
	v_readfirstlane_b32 s57, v1
	v_and_b32_e32 v143, 7, v142
	v_lshrrev_b32_e32 v144, 3, v142
	v_lshlrev_b32_e32 v145, 1, v144
	v_lshl_add_u32 v145, s6, 4, v145
	v_lshlrev_b32_e32 v182, 5, v143
	v_add_u32_e32 v140, s10, v182
	v_lshl_add_u32 v141, v145, 2, s10
	v_lshl_add_u32 v146, v144, 3, v143
	s_lshl_b32 s2, s6, 12
	s_add_i32 s2, s2, s10
	s_add_i32 s2, s2, 0xc700
	v_lshl_add_u32 v134, v146, 2, s2
	v_lshrrev_b32_e32 v146, 4, v142
	v_and_b32_e32 v147, 15, v142
	v_and_b32_e32 v148, 1, v147
	v_lshlrev_b32_e32 v148, 6, v148
	v_lshl_add_u32 v148, v146, 7, v148
	v_lshrrev_b32_e32 v180, 1, v147
	v_lshl_add_u32 v148, v180, 3, v148
	v_lshl_add_u32 v135, v148, 2, s2
	v_lshl_add_u32 v184, v145, 8, v182
	s_mov_b32 s70, 0
.Lst_seg:
	s_cmp_eq_u32 s70, 0
	s_movk_i32 s71, 0x200
	s_cselect_b32 s71, 0x100, s71
	s_movk_i32 s72, 0x100
	s_cselect_b32 s72, 0x1000, s72
	s_cselect_b32 s73, 0x100, 16
	s_mov_b32 s19, s78
	s_cmp_ge_i32 s19, s71
	s_cbranch_scc1 .Lst_seg_next
.Lst_item:
	s_lshr_b32 s27, s19, 5
	s_bfe_u32 s28, s19, 0x40001
	s_and_b32 s29, s19, 1
	s_lshl_b32 s2, s27, 12
	s_add_i32 s2, s2, 0x1000
	s_lshl_b32 s3, s27, 8
	s_cmp_eq_u32 s70, 0
	s_cselect_b32 s26, s2, s3
	s_lshl_b32 s2, s27, 2
	s_and_b32 s3, s14, -2
	s_add_i32 s2, s2, s3
	s_or_b32 s2, s2, s29
	s_lshl_b32 s2, s2, 4
	s_or_b32 s2, s2, s28
	s_mov_b32 s3, 0
	s_lshl_b64 s[40:41], s[2:3], 14
	s_cmp_eq_u32 s70, 0
	s_cbranch_scc0 .Lst_zero
	s_add_u32 s4, s56, s40
	s_addc_u32 s5, s57, s41
	v_lshl_add_u64 v[182:183], v[184:185], 0, s[4:5]
	global_load_dwordx4 v[164:167], v[182:183], off
	global_load_dwordx4 v[168:171], v[182:183], off offset:16
	global_load_dwordx4 v[172:175], v[182:183], off offset:256
	global_load_dwordx4 v[176:179], v[182:183], off offset:272
	s_waitcnt vmcnt(0)
	v_mov_b32_e32 v0, v164
	v_mov_b32_e32 v1, v172
	v_mov_b32_e32 v2, v165
	v_mov_b32_e32 v3, v173
	v_mov_b32_e32 v4, v166
	v_mov_b32_e32 v5, v174
	v_mov_b32_e32 v6, v167
	v_mov_b32_e32 v7, v175
	v_mov_b32_e32 v8, v168
	v_mov_b32_e32 v9, v176
	v_mov_b32_e32 v10, v169
	v_mov_b32_e32 v11, v177
	v_mov_b32_e32 v12, v170
	v_mov_b32_e32 v13, v178
	v_mov_b32_e32 v14, v171
	v_mov_b32_e32 v15, v179
	s_branch .Lst_init_done
.Lst_zero:
	v_mov_b32_e32 v0, 0
	v_mov_b32_e32 v1, 0
	v_mov_b32_e32 v2, 0
	v_mov_b32_e32 v3, 0
	v_mov_b32_e32 v4, 0
	v_mov_b32_e32 v5, 0
	v_mov_b32_e32 v6, 0
	v_mov_b32_e32 v7, 0
	v_mov_b32_e32 v8, 0
	v_mov_b32_e32 v9, 0
	v_mov_b32_e32 v10, 0
	v_mov_b32_e32 v11, 0
	v_mov_b32_e32 v12, 0
	v_mov_b32_e32 v13, 0
	v_mov_b32_e32 v14, 0
	v_mov_b32_e32 v15, 0
.Lst_init_done:
	s_lshl_b32 s2, s28, 6
	s_lshl_b32 s3, s6, 4
	s_add_i32 s2, s2, s3
	s_lshl_b32 s2, s2, 2
	s_add_u32 s4, s54, 0x12400000
	s_addc_u32 s5, s55, 0
	s_add_u32 s4, s4, s2
	s_addc_u32 s5, s5, 0
	s_cmp_eq_u32 s29, 0
	s_mov_b32 s38, 0xffff8000
	s_cselect_b32 s38, 0x8000, s38
	s_cselect_b32 s39, 0, -1
	s_mov_b32 s16, 0xffffc000
	s_cselect_b32 s16, 0x4000, s16
	s_cselect_b32 s17, 0, -1
	s_add_i32 s0, s72, -1
	v_sub_u32_e32 v180, s0, v146
	s_cmp_eq_u32 s29, 0
	s_cselect_b64 s[2:3], -1, 0
	v_cndmask_b32_e64 v180, v180, v146, s[2:3]
	v_add_u32_e32 v180, s26, v180
	v_lshlrev_b32_e32 v186, 12, v180
	v_lshl_add_u32 v186, v147, 2, v186
	v_lshl_add_u64 v[136:137], v[186:187], 0, s[4:5]
	v_lshl_add_u64 v[138:139], v[136:137], 0, s[16:17]
	s_mov_b32 s74, 0
	s_mov_b32 s75, 0x6100
	s_waitcnt lgkmcnt(0)
	s_barrier
.Lst_chunk:
	v_add_u32_e32 v132, s75, v140
	v_add_u32_e32 v133, s75, v141
	ds_read_b128 v[40:43], v132 offset:256
	ds_read_b128 v[44:47], v132 offset:272
	ds_read_b128 v[48:51], v132 offset:512
	ds_read_b128 v[52:55], v132 offset:528
	ds_read_b128 v[56:59], v132 offset:768
	ds_read_b128 v[60:63], v132 offset:784
	ds_read_b128 v[64:67], v132 offset:1024
	ds_read_b128 v[68:71], v132 offset:1040
	ds_read_b64 v[72:73], v133 offset:1280
	ds_read_b128 v[74:77], v132 offset:1808
	ds_read_b128 v[78:81], v132 offset:1824
	ds_read_b128 v[82:85], v132 offset:2064
	ds_read_b128 v[86:89], v132 offset:2080
	ds_read_b128 v[90:93], v132 offset:2320
	ds_read_b128 v[94:97], v132 offset:2336
	ds_read_b128 v[98:101], v132 offset:2576
	ds_read_b128 v[102:105], v132 offset:2592
	ds_read_b64 v[106:107], v133 offset:2832
	s_waitcnt lgkmcnt(9)
	v_pk_mul_f32 v[32:33], v[0:1], v[40:41] op_sel_hi:[1,0]
	v_pk_mul_f32 v[34:35], v[2:3], v[40:41] op_sel:[0,1]
	v_pk_fma_f32 v[32:33], v[4:5], v[42:43], v[32:33] op_sel_hi:[1,0,1]
	v_pk_fma_f32 v[34:35], v[6:7], v[42:43], v[34:35] op_sel:[0,1,0]
	v_pk_fma_f32 v[32:33], v[8:9], v[44:45], v[32:33] op_sel_hi:[1,0,1]
	v_pk_fma_f32 v[34:35], v[10:11], v[44:45], v[34:35] op_sel:[0,1,0]
	v_pk_fma_f32 v[32:33], v[12:13], v[46:47], v[32:33] op_sel_hi:[1,0,1]
	v_pk_fma_f32 v[34:35], v[14:15], v[46:47], v[34:35] op_sel:[0,1,0]
	v_pk_add_f32 v[32:33], v[32:33], v[34:35]
	s_nop 1
	v_add_f32_dpp v32, v32, v32 row_half_mirror row_mask:0xf bank_mask:0xf bound_ctrl:1
	v_add_f32_dpp v33, v33, v33 row_half_mirror row_mask:0xf bank_mask:0xf bound_ctrl:1
	v_pk_fma_f32 v[16:17], v[72:73], v[56:57], v[0:1] op_sel_hi:[1,0,1]
	v_add_f32_dpp v32, v32, v32 quad_perm:[1,0,3,2] row_mask:0xf bank_mask:0xf bound_ctrl:1
	v_add_f32_dpp v33, v33, v33 quad_perm:[1,0,3,2] row_mask:0xf bank_mask:0xf bound_ctrl:1
	v_pk_fma_f32 v[18:19], v[72:73], v[56:57], v[2:3] op_sel:[0,1,0]
	v_add_f32_dpp v32, v32, v32 quad_perm:[2,3,0,1] row_mask:0xf bank_mask:0xf bound_ctrl:1
	v_add_f32_dpp v33, v33, v33 quad_perm:[2,3,0,1] row_mask:0xf bank_mask:0xf bound_ctrl:1
	v_pk_fma_f32 v[20:21], v[72:73], v[58:59], v[4:5] op_sel_hi:[1,0,1]
	v_pk_fma_f32 v[22:23], v[72:73], v[58:59], v[6:7] op_sel:[0,1,0]
	v_pk_fma_f32 v[24:25], v[72:73], v[60:61], v[8:9] op_sel_hi:[1,0,1]
	v_pk_fma_f32 v[26:27], v[72:73], v[60:61], v[10:11] op_sel:[0,1,0]
	v_pk_fma_f32 v[28:29], v[72:73], v[62:63], v[12:13] op_sel_hi:[1,0,1]
	v_pk_fma_f32 v[30:31], v[72:73], v[62:63], v[14:15] op_sel:[0,1,0]
	v_pk_fma_f32 v[0:1], v[32:33], v[48:49], v[16:17] op_sel_hi:[1,0,1]
	v_pk_fma_f32 v[2:3], v[32:33], v[48:49], v[18:19] op_sel:[0,1,0]
	v_pk_fma_f32 v[4:5], v[32:33], v[50:51], v[20:21] op_sel_hi:[1,0,1]
	v_pk_fma_f32 v[6:7], v[32:33], v[50:51], v[22:23] op_sel:[0,1,0]
	v_pk_fma_f32 v[8:9], v[32:33], v[52:53], v[24:25] op_sel_hi:[1,0,1]
	v_pk_fma_f32 v[10:11], v[32:33], v[52:53], v[26:27] op_sel:[0,1,0]
	v_pk_fma_f32 v[12:13], v[32:33], v[54:55], v[28:29] op_sel_hi:[1,0,1]
	v_pk_fma_f32 v[14:15], v[32:33], v[54:55], v[30:31] op_sel:[0,1,0]
	s_waitcnt lgkmcnt(0)
	v_pk_mul_f32 v[32:33], v[0:1], v[74:75] op_sel_hi:[1,0]
	v_pk_mul_f32 v[36:37], v[0:1], v[64:65] op_sel_hi:[1,0]
	v_pk_mul_f32 v[34:35], v[2:3], v[74:75] op_sel:[0,1]
	v_pk_mul_f32 v[38:39], v[2:3], v[64:65] op_sel:[0,1]
	v_pk_fma_f32 v[32:33], v[4:5], v[76:77], v[32:33] op_sel_hi:[1,0,1]
	v_pk_fma_f32 v[36:37], v[4:5], v[66:67], v[36:37] op_sel_hi:[1,0,1]
	v_pk_fma_f32 v[34:35], v[6:7], v[76:77], v[34:35] op_sel:[0,1,0]
	v_pk_fma_f32 v[38:39], v[6:7], v[66:67], v[38:39] op_sel:[0,1,0]
	v_pk_fma_f32 v[32:33], v[8:9], v[78:79], v[32:33] op_sel_hi:[1,0,1]
	v_pk_fma_f32 v[36:37], v[8:9], v[68:69], v[36:37] op_sel_hi:[1,0,1]
	v_pk_fma_f32 v[34:35], v[10:11], v[78:79], v[34:35] op_sel:[0,1,0]
	v_pk_fma_f32 v[38:39], v[10:11], v[68:69], v[38:39] op_sel:[0,1,0]
	v_pk_fma_f32 v[32:33], v[12:13], v[80:81], v[32:33] op_sel_hi:[1,0,1]
	v_pk_fma_f32 v[36:37], v[12:13], v[70:71], v[36:37] op_sel_hi:[1,0,1]
	v_pk_fma_f32 v[34:35], v[14:15], v[80:81], v[34:35] op_sel:[0,1,0]
	v_pk_fma_f32 v[38:39], v[14:15], v[70:71], v[38:39] op_sel:[0,1,0]
	v_pk_add_f32 v[36:37], v[36:37], v[38:39]
	v_pk_add_f32 v[32:33], v[32:33], v[34:35]
	ds_write2st64_b32 v134, v36, v37 offset0:0 offset1:1
	ds_read_b128 v[40:43], v132 offset:3360
	ds_read_b128 v[44:47], v132 offset:3376
	ds_read_b128 v[48:51], v132 offset:3616
	ds_read_b128 v[52:55], v132 offset:3632
	ds_read_b128 v[56:59], v132 offset:3872
	ds_read_b128 v[60:63], v132 offset:3888
	ds_read_b128 v[64:67], v132 offset:4128
	ds_read_b128 v[68:71], v132 offset:4144
	ds_read_b64 v[72:73], v133 offset:4384
	v_add_f32_dpp v32, v32, v32 row_half_mirror row_mask:0xf bank_mask:0xf bound_ctrl:1
	v_add_f32_dpp v33, v33, v33 row_half_mirror row_mask:0xf bank_mask:0xf bound_ctrl:1
	v_pk_fma_f32 v[16:17], v[106:107], v[90:91], v[0:1] op_sel_hi:[1,0,1]
	v_add_f32_dpp v32, v32, v32 quad_perm:[1,0,3,2] row_mask:0xf bank_mask:0xf bound_ctrl:1
	v_add_f32_dpp v33, v33, v33 quad_perm:[1,0,3,2] row_mask:0xf bank_mask:0xf bound_ctrl:1
	v_pk_fma_f32 v[18:19], v[106:107], v[90:91], v[2:3] op_sel:[0,1,0]
	v_add_f32_dpp v32, v32, v32 quad_perm:[2,3,0,1] row_mask:0xf bank_mask:0xf bound_ctrl:1
	v_add_f32_dpp v33, v33, v33 quad_perm:[2,3,0,1] row_mask:0xf bank_mask:0xf bound_ctrl:1
	v_pk_fma_f32 v[20:21], v[106:107], v[92:93], v[4:5] op_sel_hi:[1,0,1]
	v_pk_fma_f32 v[22:23], v[106:107], v[92:93], v[6:7] op_sel:[0,1,0]
	v_pk_fma_f32 v[24:25], v[106:107], v[94:95], v[8:9] op_sel_hi:[1,0,1]
	v_pk_fma_f32 v[26:27], v[106:107], v[94:95], v[10:11] op_sel:[0,1,0]
	v_pk_fma_f32 v[28:29], v[106:107], v[96:97], v[12:13] op_sel_hi:[1,0,1]
	v_pk_fma_f32 v[30:31], v[106:107], v[96:97], v[14:15] op_sel:[0,1,0]
	v_pk_fma_f32 v[0:1], v[32:33], v[82:83], v[16:17] op_sel_hi:[1,0,1]
	v_pk_fma_f32 v[2:3], v[32:33], v[82:83], v[18:19] op_sel:[0,1,0]
	v_pk_fma_f32 v[4:5], v[32:33], v[84:85], v[20:21] op_sel_hi:[1,0,1]
	v_pk_fma_f32 v[6:7], v[32:33], v[84:85], v[22:23] op_sel:[0,1,0]
	v_pk_fma_f32 v[8:9], v[32:33], v[86:87], v[24:25] op_sel_hi:[1,0,1]
	v_pk_fma_f32 v[10:11], v[32:33], v[86:87], v[26:27] op_sel:[0,1,0]
	v_pk_fma_f32 v[12:13], v[32:33], v[88:89], v[28:29] op_sel_hi:[1,0,1]
	v_pk_fma_f32 v[14:15], v[32:33], v[88:89], v[30:31] op_sel:[0,1,0]
	s_waitcnt lgkmcnt(0)
	v_pk_mul_f32 v[32:33], v[0:1], v[40:41] op_sel_hi:[1,0]
	v_pk_mul_f32 v[36:37], v[0:1], v[98:99] op_sel_hi:[1,0]
	v_pk_mul_f32 v[34:35], v[2:3], v[40:41] op_sel:[0,1]
	v_pk_mul_f32 v[38:39], v[2:3], v[98:99] op_sel:[0,1]
	v_pk_fma_f32 v[32:33], v[4:5], v[42:43], v[32:33] op_sel_hi:[1,0,1]
	v_pk_fma_f32 v[36:37], v[4:5], v[100:101], v[36:37] op_sel_hi:[1,0,1]
	v_pk_fma_f32 v[34:35], v[6:7], v[42:43], v[34:35] op_sel:[0,1,0]
	v_pk_fma_f32 v[38:39], v[6:7], v[100:101], v[38:39] op_sel:[0,1,0]
	v_pk_fma_f32 v[32:33], v[8:9], v[44:45], v[32:33] op_sel_hi:[1,0,1]
	v_pk_fma_f32 v[36:37], v[8:9], v[102:103], v[36:37] op_sel_hi:[1,0,1]
	v_pk_fma_f32 v[34:35], v[10:11], v[44:45], v[34:35] op_sel:[0,1,0]
	v_pk_fma_f32 v[38:39], v[10:11], v[102:103], v[38:39] op_sel:[0,1,0]
	v_pk_fma_f32 v[32:33], v[12:13], v[46:47], v[32:33] op_sel_hi:[1,0,1]
	v_pk_fma_f32 v[36:37], v[12:13], v[104:105], v[36:37] op_sel_hi:[1,0,1]
	v_pk_fma_f32 v[34:35], v[14:15], v[46:47], v[34:35] op_sel:[0,1,0]
	v_pk_fma_f32 v[38:39], v[14:15], v[104:105], v[38:39] op_sel:[0,1,0]
	v_pk_add_f32 v[36:37], v[36:37], v[38:39]
	v_pk_add_f32 v[32:33], v[32:33], v[34:35]
	ds_write2st64_b32 v134, v36, v37 offset0:2 offset1:3
	ds_read_b128 v[74:77], v132 offset:4912
	ds_read_b128 v[78:81], v132 offset:4928
	ds_read_b128 v[82:85], v132 offset:5168
	ds_read_b128 v[86:89], v132 offset:5184
	ds_read_b128 v[90:93], v132 offset:5424
	ds_read_b128 v[94:97], v132 offset:5440
	ds_read_b128 v[98:101], v132 offset:5680
	ds_read_b128 v[102:105], v132 offset:5696
	ds_read_b64 v[106:107], v133 offset:5936
	v_add_f32_dpp v32, v32, v32 row_half_mirror row_mask:0xf bank_mask:0xf bound_ctrl:1
	v_add_f32_dpp v33, v33, v33 row_half_mirror row_mask:0xf bank_mask:0xf bound_ctrl:1
	v_pk_fma_f32 v[16:17], v[72:73], v[56:57], v[0:1] op_sel_hi:[1,0,1]
	v_add_f32_dpp v32, v32, v32 quad_perm:[1,0,3,2] row_mask:0xf bank_mask:0xf bound_ctrl:1
	v_add_f32_dpp v33, v33, v33 quad_perm:[1,0,3,2] row_mask:0xf bank_mask:0xf bound_ctrl:1
	v_pk_fma_f32 v[18:19], v[72:73], v[56:57], v[2:3] op_sel:[0,1,0]
	v_add_f32_dpp v32, v32, v32 quad_perm:[2,3,0,1] row_mask:0xf bank_mask:0xf bound_ctrl:1
	v_add_f32_dpp v33, v33, v33 quad_perm:[2,3,0,1] row_mask:0xf bank_mask:0xf bound_ctrl:1
	v_pk_fma_f32 v[20:21], v[72:73], v[58:59], v[4:5] op_sel_hi:[1,0,1]
	v_pk_fma_f32 v[22:23], v[72:73], v[58:59], v[6:7] op_sel:[0,1,0]
	v_pk_fma_f32 v[24:25], v[72:73], v[60:61], v[8:9] op_sel_hi:[1,0,1]
	v_pk_fma_f32 v[26:27], v[72:73], v[60:61], v[10:11] op_sel:[0,1,0]
	v_pk_fma_f32 v[28:29], v[72:73], v[62:63], v[12:13] op_sel_hi:[1,0,1]
	v_pk_fma_f32 v[30:31], v[72:73], v[62:63], v[14:15] op_sel:[0,1,0]
	v_pk_fma_f32 v[0:1], v[32:33], v[48:49], v[16:17] op_sel_hi:[1,0,1]
	v_pk_fma_f32 v[2:3], v[32:33], v[48:49], v[18:19] op_sel:[0,1,0]
	v_pk_fma_f32 v[4:5], v[32:33], v[50:51], v[20:21] op_sel_hi:[1,0,1]
	v_pk_fma_f32 v[6:7], v[32:33], v[50:51], v[22:23] op_sel:[0,1,0]
	v_pk_fma_f32 v[8:9], v[32:33], v[52:53], v[24:25] op_sel_hi:[1,0,1]
	v_pk_fma_f32 v[10:11], v[32:33], v[52:53], v[26:27] op_sel:[0,1,0]
	v_pk_fma_f32 v[12:13], v[32:33], v[54:55], v[28:29] op_sel_hi:[1,0,1]
	v_pk_fma_f32 v[14:15], v[32:33], v[54:55], v[30:31] op_sel:[0,1,0]
	s_waitcnt lgkmcnt(0)
	v_pk_mul_f32 v[32:33], v[0:1], v[74:75] op_sel_hi:[1,0]
	v_pk_mul_f32 v[36:37], v[0:1], v[64:65] op_sel_hi:[1,0]
	v_pk_mul_f32 v[34:35], v[2:3], v[74:75] op_sel:[0,1]
	v_pk_mul_f32 v[38:39], v[2:3], v[64:65] op_sel:[0,1]
	v_pk_fma_f32 v[32:33], v[4:5], v[76:77], v[32:33] op_sel_hi:[1,0,1]
	v_pk_fma_f32 v[36:37], v[4:5], v[66:67], v[36:37] op_sel_hi:[1,0,1]
	v_pk_fma_f32 v[34:35], v[6:7], v[76:77], v[34:35] op_sel:[0,1,0]
	v_pk_fma_f32 v[38:39], v[6:7], v[66:67], v[38:39] op_sel:[0,1,0]
	v_pk_fma_f32 v[32:33], v[8:9], v[78:79], v[32:33] op_sel_hi:[1,0,1]
	v_pk_fma_f32 v[36:37], v[8:9], v[68:69], v[36:37] op_sel_hi:[1,0,1]
	v_pk_fma_f32 v[34:35], v[10:11], v[78:79], v[34:35] op_sel:[0,1,0]
	v_pk_fma_f32 v[38:39], v[10:11], v[68:69], v[38:39] op_sel:[0,1,0]
	v_pk_fma_f32 v[32:33], v[12:13], v[80:81], v[32:33] op_sel_hi:[1,0,1]
	v_pk_fma_f32 v[36:37], v[12:13], v[70:71], v[36:37] op_sel_hi:[1,0,1]
	v_pk_fma_f32 v[34:35], v[14:15], v[80:81], v[34:35] op_sel:[0,1,0]
	v_pk_fma_f32 v[38:39], v[14:15], v[70:71], v[38:39] op_sel:[0,1,0]
	v_pk_add_f32 v[36:37], v[36:37], v[38:39]
	v_pk_add_f32 v[32:33], v[32:33], v[34:35]
	ds_write2st64_b32 v134, v36, v37 offset0:4 offset1:5
	ds_read_b128 v[40:43], v132 offset:6464
	ds_read_b128 v[44:47], v132 offset:6480
	ds_read_b128 v[48:51], v132 offset:6720
	ds_read_b128 v[52:55], v132 offset:6736
	ds_read_b128 v[56:59], v132 offset:6976
	ds_read_b128 v[60:63], v132 offset:6992
	ds_read_b128 v[64:67], v132 offset:7232
	ds_read_b128 v[68:71], v132 offset:7248
	ds_read_b64 v[72:73], v133 offset:7488
	v_add_f32_dpp v32, v32, v32 row_half_mirror row_mask:0xf bank_mask:0xf bound_ctrl:1
	v_add_f32_dpp v33, v33, v33 row_half_mirror row_mask:0xf bank_mask:0xf bound_ctrl:1
	v_pk_fma_f32 v[16:17], v[106:107], v[90:91], v[0:1] op_sel_hi:[1,0,1]
	v_add_f32_dpp v32, v32, v32 quad_perm:[1,0,3,2] row_mask:0xf bank_mask:0xf bound_ctrl:1
	v_add_f32_dpp v33, v33, v33 quad_perm:[1,0,3,2] row_mask:0xf bank_mask:0xf bound_ctrl:1
	v_pk_fma_f32 v[18:19], v[106:107], v[90:91], v[2:3] op_sel:[0,1,0]
	v_add_f32_dpp v32, v32, v32 quad_perm:[2,3,0,1] row_mask:0xf bank_mask:0xf bound_ctrl:1
	v_add_f32_dpp v33, v33, v33 quad_perm:[2,3,0,1] row_mask:0xf bank_mask:0xf bound_ctrl:1
	v_pk_fma_f32 v[20:21], v[106:107], v[92:93], v[4:5] op_sel_hi:[1,0,1]
	v_pk_fma_f32 v[22:23], v[106:107], v[92:93], v[6:7] op_sel:[0,1,0]
	v_pk_fma_f32 v[24:25], v[106:107], v[94:95], v[8:9] op_sel_hi:[1,0,1]
	v_pk_fma_f32 v[26:27], v[106:107], v[94:95], v[10:11] op_sel:[0,1,0]
	v_pk_fma_f32 v[28:29], v[106:107], v[96:97], v[12:13] op_sel_hi:[1,0,1]
	v_pk_fma_f32 v[30:31], v[106:107], v[96:97], v[14:15] op_sel:[0,1,0]
	v_pk_fma_f32 v[0:1], v[32:33], v[82:83], v[16:17] op_sel_hi:[1,0,1]
	v_pk_fma_f32 v[2:3], v[32:33], v[82:83], v[18:19] op_sel:[0,1,0]
	v_pk_fma_f32 v[4:5], v[32:33], v[84:85], v[20:21] op_sel_hi:[1,0,1]
	v_pk_fma_f32 v[6:7], v[32:33], v[84:85], v[22:23] op_sel:[0,1,0]
	v_pk_fma_f32 v[8:9], v[32:33], v[86:87], v[24:25] op_sel_hi:[1,0,1]
	v_pk_fma_f32 v[10:11], v[32:33], v[86:87], v[26:27] op_sel:[0,1,0]
	v_pk_fma_f32 v[12:13], v[32:33], v[88:89], v[28:29] op_sel_hi:[1,0,1]
	v_pk_fma_f32 v[14:15], v[32:33], v[88:89], v[30:31] op_sel:[0,1,0]
	s_waitcnt lgkmcnt(0)
	v_pk_mul_f32 v[32:33], v[0:1], v[40:41] op_sel_hi:[1,0]
	v_pk_mul_f32 v[36:37], v[0:1], v[98:99] op_sel_hi:[1,0]
	v_pk_mul_f32 v[34:35], v[2:3], v[40:41] op_sel:[0,1]
	v_pk_mul_f32 v[38:39], v[2:3], v[98:99] op_sel:[0,1]
	v_pk_fma_f32 v[32:33], v[4:5], v[42:43], v[32:33] op_sel_hi:[1,0,1]
	v_pk_fma_f32 v[36:37], v[4:5], v[100:101], v[36:37] op_sel_hi:[1,0,1]
	v_pk_fma_f32 v[34:35], v[6:7], v[42:43], v[34:35] op_sel:[0,1,0]
	v_pk_fma_f32 v[38:39], v[6:7], v[100:101], v[38:39] op_sel:[0,1,0]
	v_pk_fma_f32 v[32:33], v[8:9], v[44:45], v[32:33] op_sel_hi:[1,0,1]
	v_pk_fma_f32 v[36:37], v[8:9], v[102:103], v[36:37] op_sel_hi:[1,0,1]
	v_pk_fma_f32 v[34:35], v[10:11], v[44:45], v[34:35] op_sel:[0,1,0]
	v_pk_fma_f32 v[38:39], v[10:11], v[102:103], v[38:39] op_sel:[0,1,0]
	v_pk_fma_f32 v[32:33], v[12:13], v[46:47], v[32:33] op_sel_hi:[1,0,1]
	v_pk_fma_f32 v[36:37], v[12:13], v[104:105], v[36:37] op_sel_hi:[1,0,1]
	v_pk_fma_f32 v[34:35], v[14:15], v[46:47], v[34:35] op_sel:[0,1,0]
	v_pk_fma_f32 v[38:39], v[14:15], v[104:105], v[38:39] op_sel:[0,1,0]
	v_pk_add_f32 v[36:37], v[36:37], v[38:39]
	v_pk_add_f32 v[32:33], v[32:33], v[34:35]
	ds_write2st64_b32 v134, v36, v37 offset0:6 offset1:7
	ds_read_b128 v[74:77], v132 offset:8016
	ds_read_b128 v[78:81], v132 offset:8032
	ds_read_b128 v[82:85], v132 offset:8272
	ds_read_b128 v[86:89], v132 offset:8288
	ds_read_b128 v[90:93], v132 offset:8528
	ds_read_b128 v[94:97], v132 offset:8544
	ds_read_b128 v[98:101], v132 offset:8784
	ds_read_b128 v[102:105], v132 offset:8800
	ds_read_b64 v[106:107], v133 offset:9040
	v_add_f32_dpp v32, v32, v32 row_half_mirror row_mask:0xf bank_mask:0xf bound_ctrl:1
	v_add_f32_dpp v33, v33, v33 row_half_mirror row_mask:0xf bank_mask:0xf bound_ctrl:1
	v_pk_fma_f32 v[16:17], v[72:73], v[56:57], v[0:1] op_sel_hi:[1,0,1]
	v_add_f32_dpp v32, v32, v32 quad_perm:[1,0,3,2] row_mask:0xf bank_mask:0xf bound_ctrl:1
	v_add_f32_dpp v33, v33, v33 quad_perm:[1,0,3,2] row_mask:0xf bank_mask:0xf bound_ctrl:1
	v_pk_fma_f32 v[18:19], v[72:73], v[56:57], v[2:3] op_sel:[0,1,0]
	v_add_f32_dpp v32, v32, v32 quad_perm:[2,3,0,1] row_mask:0xf bank_mask:0xf bound_ctrl:1
	v_add_f32_dpp v33, v33, v33 quad_perm:[2,3,0,1] row_mask:0xf bank_mask:0xf bound_ctrl:1
	v_pk_fma_f32 v[20:21], v[72:73], v[58:59], v[4:5] op_sel_hi:[1,0,1]
	v_pk_fma_f32 v[22:23], v[72:73], v[58:59], v[6:7] op_sel:[0,1,0]
	v_pk_fma_f32 v[24:25], v[72:73], v[60:61], v[8:9] op_sel_hi:[1,0,1]
	v_pk_fma_f32 v[26:27], v[72:73], v[60:61], v[10:11] op_sel:[0,1,0]
	v_pk_fma_f32 v[28:29], v[72:73], v[62:63], v[12:13] op_sel_hi:[1,0,1]
	v_pk_fma_f32 v[30:31], v[72:73], v[62:63], v[14:15] op_sel:[0,1,0]
	v_pk_fma_f32 v[0:1], v[32:33], v[48:49], v[16:17] op_sel_hi:[1,0,1]
	v_pk_fma_f32 v[2:3], v[32:33], v[48:49], v[18:19] op_sel:[0,1,0]
	v_pk_fma_f32 v[4:5], v[32:33], v[50:51], v[20:21] op_sel_hi:[1,0,1]
	v_pk_fma_f32 v[6:7], v[32:33], v[50:51], v[22:23] op_sel:[0,1,0]
	v_pk_fma_f32 v[8:9], v[32:33], v[52:53], v[24:25] op_sel_hi:[1,0,1]
	v_pk_fma_f32 v[10:11], v[32:33], v[52:53], v[26:27] op_sel:[0,1,0]
	v_pk_fma_f32 v[12:13], v[32:33], v[54:55], v[28:29] op_sel_hi:[1,0,1]
	v_pk_fma_f32 v[14:15], v[32:33], v[54:55], v[30:31] op_sel:[0,1,0]
	s_waitcnt lgkmcnt(0)
	v_pk_mul_f32 v[32:33], v[0:1], v[74:75] op_sel_hi:[1,0]
	v_pk_mul_f32 v[36:37], v[0:1], v[64:65] op_sel_hi:[1,0]
	v_pk_mul_f32 v[34:35], v[2:3], v[74:75] op_sel:[0,1]
	v_pk_mul_f32 v[38:39], v[2:3], v[64:65] op_sel:[0,1]
	v_pk_fma_f32 v[32:33], v[4:5], v[76:77], v[32:33] op_sel_hi:[1,0,1]
	v_pk_fma_f32 v[36:37], v[4:5], v[66:67], v[36:37] op_sel_hi:[1,0,1]
	v_pk_fma_f32 v[34:35], v[6:7], v[76:77], v[34:35] op_sel:[0,1,0]
	v_pk_fma_f32 v[38:39], v[6:7], v[66:67], v[38:39] op_sel:[0,1,0]
	v_pk_fma_f32 v[32:33], v[8:9], v[78:79], v[32:33] op_sel_hi:[1,0,1]
	v_pk_fma_f32 v[36:37], v[8:9], v[68:69], v[36:37] op_sel_hi:[1,0,1]
	v_pk_fma_f32 v[34:35], v[10:11], v[78:79], v[34:35] op_sel:[0,1,0]
	v_pk_fma_f32 v[38:39], v[10:11], v[68:69], v[38:39] op_sel:[0,1,0]
	v_pk_fma_f32 v[32:33], v[12:13], v[80:81], v[32:33] op_sel_hi:[1,0,1]
	v_pk_fma_f32 v[36:37], v[12:13], v[70:71], v[36:37] op_sel_hi:[1,0,1]
	v_pk_fma_f32 v[34:35], v[14:15], v[80:81], v[34:35] op_sel:[0,1,0]
	v_pk_fma_f32 v[38:39], v[14:15], v[70:71], v[38:39] op_sel:[0,1,0]
	v_pk_add_f32 v[36:37], v[36:37], v[38:39]
	v_pk_add_f32 v[32:33], v[32:33], v[34:35]
	ds_write2st64_b32 v134, v36, v37 offset0:8 offset1:9
	ds_read_b128 v[40:43], v132 offset:9568
	ds_read_b128 v[44:47], v132 offset:9584
	ds_read_b128 v[48:51], v132 offset:9824
	ds_read_b128 v[52:55], v132 offset:9840
	ds_read_b128 v[56:59], v132 offset:10080
	ds_read_b128 v[60:63], v132 offset:10096
	ds_read_b128 v[64:67], v132 offset:10336
	ds_read_b128 v[68:71], v132 offset:10352
	ds_read_b64 v[72:73], v133 offset:10592
	v_add_f32_dpp v32, v32, v32 row_half_mirror row_mask:0xf bank_mask:0xf bound_ctrl:1
	v_add_f32_dpp v33, v33, v33 row_half_mirror row_mask:0xf bank_mask:0xf bound_ctrl:1
	v_pk_fma_f32 v[16:17], v[106:107], v[90:91], v[0:1] op_sel_hi:[1,0,1]
	v_add_f32_dpp v32, v32, v32 quad_perm:[1,0,3,2] row_mask:0xf bank_mask:0xf bound_ctrl:1
	v_add_f32_dpp v33, v33, v33 quad_perm:[1,0,3,2] row_mask:0xf bank_mask:0xf bound_ctrl:1
	v_pk_fma_f32 v[18:19], v[106:107], v[90:91], v[2:3] op_sel:[0,1,0]
	v_add_f32_dpp v32, v32, v32 quad_perm:[2,3,0,1] row_mask:0xf bank_mask:0xf bound_ctrl:1
	v_add_f32_dpp v33, v33, v33 quad_perm:[2,3,0,1] row_mask:0xf bank_mask:0xf bound_ctrl:1
	v_pk_fma_f32 v[20:21], v[106:107], v[92:93], v[4:5] op_sel_hi:[1,0,1]
	v_pk_fma_f32 v[22:23], v[106:107], v[92:93], v[6:7] op_sel:[0,1,0]
	v_pk_fma_f32 v[24:25], v[106:107], v[94:95], v[8:9] op_sel_hi:[1,0,1]
	v_pk_fma_f32 v[26:27], v[106:107], v[94:95], v[10:11] op_sel:[0,1,0]
	v_pk_fma_f32 v[28:29], v[106:107], v[96:97], v[12:13] op_sel_hi:[1,0,1]
	v_pk_fma_f32 v[30:31], v[106:107], v[96:97], v[14:15] op_sel:[0,1,0]
	v_pk_fma_f32 v[0:1], v[32:33], v[82:83], v[16:17] op_sel_hi:[1,0,1]
	v_pk_fma_f32 v[2:3], v[32:33], v[82:83], v[18:19] op_sel:[0,1,0]
	v_pk_fma_f32 v[4:5], v[32:33], v[84:85], v[20:21] op_sel_hi:[1,0,1]
	v_pk_fma_f32 v[6:7], v[32:33], v[84:85], v[22:23] op_sel:[0,1,0]
	v_pk_fma_f32 v[8:9], v[32:33], v[86:87], v[24:25] op_sel_hi:[1,0,1]
	v_pk_fma_f32 v[10:11], v[32:33], v[86:87], v[26:27] op_sel:[0,1,0]
	v_pk_fma_f32 v[12:13], v[32:33], v[88:89], v[28:29] op_sel_hi:[1,0,1]
	v_pk_fma_f32 v[14:15], v[32:33], v[88:89], v[30:31] op_sel:[0,1,0]
	s_waitcnt lgkmcnt(0)
	v_pk_mul_f32 v[32:33], v[0:1], v[40:41] op_sel_hi:[1,0]
	v_pk_mul_f32 v[36:37], v[0:1], v[98:99] op_sel_hi:[1,0]
	v_pk_mul_f32 v[34:35], v[2:3], v[40:41] op_sel:[0,1]
	v_pk_mul_f32 v[38:39], v[2:3], v[98:99] op_sel:[0,1]
	v_pk_fma_f32 v[32:33], v[4:5], v[42:43], v[32:33] op_sel_hi:[1,0,1]
	v_pk_fma_f32 v[36:37], v[4:5], v[100:101], v[36:37] op_sel_hi:[1,0,1]
	v_pk_fma_f32 v[34:35], v[6:7], v[42:43], v[34:35] op_sel:[0,1,0]
	v_pk_fma_f32 v[38:39], v[6:7], v[100:101], v[38:39] op_sel:[0,1,0]
	v_pk_fma_f32 v[32:33], v[8:9], v[44:45], v[32:33] op_sel_hi:[1,0,1]
	v_pk_fma_f32 v[36:37], v[8:9], v[102:103], v[36:37] op_sel_hi:[1,0,1]
	v_pk_fma_f32 v[34:35], v[10:11], v[44:45], v[34:35] op_sel:[0,1,0]
	v_pk_fma_f32 v[38:39], v[10:11], v[102:103], v[38:39] op_sel:[0,1,0]
	v_pk_fma_f32 v[32:33], v[12:13], v[46:47], v[32:33] op_sel_hi:[1,0,1]
	v_pk_fma_f32 v[36:37], v[12:13], v[104:105], v[36:37] op_sel_hi:[1,0,1]
	v_pk_fma_f32 v[34:35], v[14:15], v[46:47], v[34:35] op_sel:[0,1,0]
	v_pk_fma_f32 v[38:39], v[14:15], v[104:105], v[38:39] op_sel:[0,1,0]
	v_pk_add_f32 v[36:37], v[36:37], v[38:39]
	v_pk_add_f32 v[32:33], v[32:33], v[34:35]
	ds_write2st64_b32 v134, v36, v37 offset0:10 offset1:11
	ds_read_b128 v[74:77], v132 offset:11120
	ds_read_b128 v[78:81], v132 offset:11136
	ds_read_b128 v[82:85], v132 offset:11376
	ds_read_b128 v[86:89], v132 offset:11392
	ds_read_b128 v[90:93], v132 offset:11632
	ds_read_b128 v[94:97], v132 offset:11648
	ds_read_b128 v[98:101], v132 offset:11888
	ds_read_b128 v[102:105], v132 offset:11904
	ds_read_b64 v[106:107], v133 offset:12144
	v_add_f32_dpp v32, v32, v32 row_half_mirror row_mask:0xf bank_mask:0xf bound_ctrl:1
	v_add_f32_dpp v33, v33, v33 row_half_mirror row_mask:0xf bank_mask:0xf bound_ctrl:1
	v_pk_fma_f32 v[16:17], v[72:73], v[56:57], v[0:1] op_sel_hi:[1,0,1]
	v_add_f32_dpp v32, v32, v32 quad_perm:[1,0,3,2] row_mask:0xf bank_mask:0xf bound_ctrl:1
	v_add_f32_dpp v33, v33, v33 quad_perm:[1,0,3,2] row_mask:0xf bank_mask:0xf bound_ctrl:1
	v_pk_fma_f32 v[18:19], v[72:73], v[56:57], v[2:3] op_sel:[0,1,0]
	v_add_f32_dpp v32, v32, v32 quad_perm:[2,3,0,1] row_mask:0xf bank_mask:0xf bound_ctrl:1
	v_add_f32_dpp v33, v33, v33 quad_perm:[2,3,0,1] row_mask:0xf bank_mask:0xf bound_ctrl:1
	v_pk_fma_f32 v[20:21], v[72:73], v[58:59], v[4:5] op_sel_hi:[1,0,1]
	v_pk_fma_f32 v[22:23], v[72:73], v[58:59], v[6:7] op_sel:[0,1,0]
	v_pk_fma_f32 v[24:25], v[72:73], v[60:61], v[8:9] op_sel_hi:[1,0,1]
	v_pk_fma_f32 v[26:27], v[72:73], v[60:61], v[10:11] op_sel:[0,1,0]
	v_pk_fma_f32 v[28:29], v[72:73], v[62:63], v[12:13] op_sel_hi:[1,0,1]
	v_pk_fma_f32 v[30:31], v[72:73], v[62:63], v[14:15] op_sel:[0,1,0]
	v_pk_fma_f32 v[0:1], v[32:33], v[48:49], v[16:17] op_sel_hi:[1,0,1]
	v_pk_fma_f32 v[2:3], v[32:33], v[48:49], v[18:19] op_sel:[0,1,0]
	v_pk_fma_f32 v[4:5], v[32:33], v[50:51], v[20:21] op_sel_hi:[1,0,1]
	v_pk_fma_f32 v[6:7], v[32:33], v[50:51], v[22:23] op_sel:[0,1,0]
	v_pk_fma_f32 v[8:9], v[32:33], v[52:53], v[24:25] op_sel_hi:[1,0,1]
	v_pk_fma_f32 v[10:11], v[32:33], v[52:53], v[26:27] op_sel:[0,1,0]
	v_pk_fma_f32 v[12:13], v[32:33], v[54:55], v[28:29] op_sel_hi:[1,0,1]
	v_pk_fma_f32 v[14:15], v[32:33], v[54:55], v[30:31] op_sel:[0,1,0]
	s_waitcnt lgkmcnt(0)
	v_pk_mul_f32 v[32:33], v[0:1], v[74:75] op_sel_hi:[1,0]
	v_pk_mul_f32 v[36:37], v[0:1], v[64:65] op_sel_hi:[1,0]
	v_pk_mul_f32 v[34:35], v[2:3], v[74:75] op_sel:[0,1]
	v_pk_mul_f32 v[38:39], v[2:3], v[64:65] op_sel:[0,1]
	v_pk_fma_f32 v[32:33], v[4:5], v[76:77], v[32:33] op_sel_hi:[1,0,1]
	v_pk_fma_f32 v[36:37], v[4:5], v[66:67], v[36:37] op_sel_hi:[1,0,1]
	v_pk_fma_f32 v[34:35], v[6:7], v[76:77], v[34:35] op_sel:[0,1,0]
	v_pk_fma_f32 v[38:39], v[6:7], v[66:67], v[38:39] op_sel:[0,1,0]
	v_pk_fma_f32 v[32:33], v[8:9], v[78:79], v[32:33] op_sel_hi:[1,0,1]
	v_pk_fma_f32 v[36:37], v[8:9], v[68:69], v[36:37] op_sel_hi:[1,0,1]
	v_pk_fma_f32 v[34:35], v[10:11], v[78:79], v[34:35] op_sel:[0,1,0]
	v_pk_fma_f32 v[38:39], v[10:11], v[68:69], v[38:39] op_sel:[0,1,0]
	v_pk_fma_f32 v[32:33], v[12:13], v[80:81], v[32:33] op_sel_hi:[1,0,1]
	v_pk_fma_f32 v[36:37], v[12:13], v[70:71], v[36:37] op_sel_hi:[1,0,1]
	v_pk_fma_f32 v[34:35], v[14:15], v[80:81], v[34:35] op_sel:[0,1,0]
	v_pk_fma_f32 v[38:39], v[14:15], v[70:71], v[38:39] op_sel:[0,1,0]
	v_pk_add_f32 v[36:37], v[36:37], v[38:39]
	v_pk_add_f32 v[32:33], v[32:33], v[34:35]
	ds_write2st64_b32 v134, v36, v37 offset0:12 offset1:13
	ds_read_b128 v[40:43], v132 offset:12672
	ds_read_b128 v[44:47], v132 offset:12688
	ds_read_b128 v[48:51], v132 offset:12928
	ds_read_b128 v[52:55], v132 offset:12944
	ds_read_b128 v[56:59], v132 offset:13184
	ds_read_b128 v[60:63], v132 offset:13200
	ds_read_b128 v[64:67], v132 offset:13440
	ds_read_b128 v[68:71], v132 offset:13456
	ds_read_b64 v[72:73], v133 offset:13696
	v_add_f32_dpp v32, v32, v32 row_half_mirror row_mask:0xf bank_mask:0xf bound_ctrl:1
	v_add_f32_dpp v33, v33, v33 row_half_mirror row_mask:0xf bank_mask:0xf bound_ctrl:1
	v_pk_fma_f32 v[16:17], v[106:107], v[90:91], v[0:1] op_sel_hi:[1,0,1]
	v_add_f32_dpp v32, v32, v32 quad_perm:[1,0,3,2] row_mask:0xf bank_mask:0xf bound_ctrl:1
	v_add_f32_dpp v33, v33, v33 quad_perm:[1,0,3,2] row_mask:0xf bank_mask:0xf bound_ctrl:1
	v_pk_fma_f32 v[18:19], v[106:107], v[90:91], v[2:3] op_sel:[0,1,0]
	v_add_f32_dpp v32, v32, v32 quad_perm:[2,3,0,1] row_mask:0xf bank_mask:0xf bound_ctrl:1
	v_add_f32_dpp v33, v33, v33 quad_perm:[2,3,0,1] row_mask:0xf bank_mask:0xf bound_ctrl:1
	v_pk_fma_f32 v[20:21], v[106:107], v[92:93], v[4:5] op_sel_hi:[1,0,1]
	v_pk_fma_f32 v[22:23], v[106:107], v[92:93], v[6:7] op_sel:[0,1,0]
	v_pk_fma_f32 v[24:25], v[106:107], v[94:95], v[8:9] op_sel_hi:[1,0,1]
	v_pk_fma_f32 v[26:27], v[106:107], v[94:95], v[10:11] op_sel:[0,1,0]
	v_pk_fma_f32 v[28:29], v[106:107], v[96:97], v[12:13] op_sel_hi:[1,0,1]
	v_pk_fma_f32 v[30:31], v[106:107], v[96:97], v[14:15] op_sel:[0,1,0]
	v_pk_fma_f32 v[0:1], v[32:33], v[82:83], v[16:17] op_sel_hi:[1,0,1]
	v_pk_fma_f32 v[2:3], v[32:33], v[82:83], v[18:19] op_sel:[0,1,0]
	v_pk_fma_f32 v[4:5], v[32:33], v[84:85], v[20:21] op_sel_hi:[1,0,1]
	v_pk_fma_f32 v[6:7], v[32:33], v[84:85], v[22:23] op_sel:[0,1,0]
	v_pk_fma_f32 v[8:9], v[32:33], v[86:87], v[24:25] op_sel_hi:[1,0,1]
	v_pk_fma_f32 v[10:11], v[32:33], v[86:87], v[26:27] op_sel:[0,1,0]
	v_pk_fma_f32 v[12:13], v[32:33], v[88:89], v[28:29] op_sel_hi:[1,0,1]
	v_pk_fma_f32 v[14:15], v[32:33], v[88:89], v[30:31] op_sel:[0,1,0]
	s_waitcnt lgkmcnt(0)
	v_pk_mul_f32 v[32:33], v[0:1], v[40:41] op_sel_hi:[1,0]
	v_pk_mul_f32 v[36:37], v[0:1], v[98:99] op_sel_hi:[1,0]
	v_pk_mul_f32 v[34:35], v[2:3], v[40:41] op_sel:[0,1]
	v_pk_mul_f32 v[38:39], v[2:3], v[98:99] op_sel:[0,1]
	v_pk_fma_f32 v[32:33], v[4:5], v[42:43], v[32:33] op_sel_hi:[1,0,1]
	v_pk_fma_f32 v[36:37], v[4:5], v[100:101], v[36:37] op_sel_hi:[1,0,1]
	v_pk_fma_f32 v[34:35], v[6:7], v[42:43], v[34:35] op_sel:[0,1,0]
	v_pk_fma_f32 v[38:39], v[6:7], v[100:101], v[38:39] op_sel:[0,1,0]
	v_pk_fma_f32 v[32:33], v[8:9], v[44:45], v[32:33] op_sel_hi:[1,0,1]
	v_pk_fma_f32 v[36:37], v[8:9], v[102:103], v[36:37] op_sel_hi:[1,0,1]
	v_pk_fma_f32 v[34:35], v[10:11], v[44:45], v[34:35] op_sel:[0,1,0]
	v_pk_fma_f32 v[38:39], v[10:11], v[102:103], v[38:39] op_sel:[0,1,0]
	v_pk_fma_f32 v[32:33], v[12:13], v[46:47], v[32:33] op_sel_hi:[1,0,1]
	v_pk_fma_f32 v[36:37], v[12:13], v[104:105], v[36:37] op_sel_hi:[1,0,1]
	v_pk_fma_f32 v[34:35], v[14:15], v[46:47], v[34:35] op_sel:[0,1,0]
	v_pk_fma_f32 v[38:39], v[14:15], v[104:105], v[38:39] op_sel:[0,1,0]
	v_pk_add_f32 v[36:37], v[36:37], v[38:39]
	v_pk_add_f32 v[32:33], v[32:33], v[34:35]
	ds_write2st64_b32 v134, v36, v37 offset0:14 offset1:15
	ds_read_b128 v[74:77], v132 offset:14224
	ds_read_b128 v[78:81], v132 offset:14240
	ds_read_b128 v[82:85], v132 offset:14480
	ds_read_b128 v[86:89], v132 offset:14496
	ds_read_b128 v[90:93], v132 offset:14736
	ds_read_b128 v[94:97], v132 offset:14752
	ds_read_b128 v[98:101], v132 offset:14992
	ds_read_b128 v[102:105], v132 offset:15008
	ds_read_b64 v[106:107], v133 offset:15248
	ds_read_b128 v[116:119], v135
	ds_read_b128 v[120:123], v135 offset:16
	ds_read_b128 v[124:127], v135 offset:2048
	ds_read_b128 v[128:131], v135 offset:2064
	s_waitcnt lgkmcnt(2)
	v_pk_add_f32 v[116:117], v[116:117], v[118:119]
	v_pk_add_f32 v[120:121], v[120:121], v[122:123]
	s_waitcnt lgkmcnt(0)
	v_pk_add_f32 v[124:125], v[124:125], v[126:127]
	v_pk_add_f32 v[128:129], v[128:129], v[130:131]
	v_pk_add_f32 v[116:117], v[116:117], v[120:121]
	v_pk_add_f32 v[124:125], v[124:125], v[128:129]
	v_add_f32_e32 v116, v116, v117
	v_add_f32_e32 v124, v124, v125
	global_atomic_add_f32 v[136:137], v116, off
	global_atomic_add_f32 v[138:139], v124, off
	v_lshl_add_u64 v[136:137], v[136:137], 0, s[38:39]
	v_lshl_add_u64 v[138:139], v[138:139], 0, s[38:39]
	v_add_f32_dpp v32, v32, v32 row_half_mirror row_mask:0xf bank_mask:0xf bound_ctrl:1
	v_add_f32_dpp v33, v33, v33 row_half_mirror row_mask:0xf bank_mask:0xf bound_ctrl:1
	v_pk_fma_f32 v[16:17], v[72:73], v[56:57], v[0:1] op_sel_hi:[1,0,1]
	v_add_f32_dpp v32, v32, v32 quad_perm:[1,0,3,2] row_mask:0xf bank_mask:0xf bound_ctrl:1
	v_add_f32_dpp v33, v33, v33 quad_perm:[1,0,3,2] row_mask:0xf bank_mask:0xf bound_ctrl:1
	v_pk_fma_f32 v[18:19], v[72:73], v[56:57], v[2:3] op_sel:[0,1,0]
	v_add_f32_dpp v32, v32, v32 quad_perm:[2,3,0,1] row_mask:0xf bank_mask:0xf bound_ctrl:1
	v_add_f32_dpp v33, v33, v33 quad_perm:[2,3,0,1] row_mask:0xf bank_mask:0xf bound_ctrl:1
	v_pk_fma_f32 v[20:21], v[72:73], v[58:59], v[4:5] op_sel_hi:[1,0,1]
	v_pk_fma_f32 v[22:23], v[72:73], v[58:59], v[6:7] op_sel:[0,1,0]
	v_pk_fma_f32 v[24:25], v[72:73], v[60:61], v[8:9] op_sel_hi:[1,0,1]
	v_pk_fma_f32 v[26:27], v[72:73], v[60:61], v[10:11] op_sel:[0,1,0]
	v_pk_fma_f32 v[28:29], v[72:73], v[62:63], v[12:13] op_sel_hi:[1,0,1]
	v_pk_fma_f32 v[30:31], v[72:73], v[62:63], v[14:15] op_sel:[0,1,0]
	v_pk_fma_f32 v[0:1], v[32:33], v[48:49], v[16:17] op_sel_hi:[1,0,1]
	v_pk_fma_f32 v[2:3], v[32:33], v[48:49], v[18:19] op_sel:[0,1,0]
	v_pk_fma_f32 v[4:5], v[32:33], v[50:51], v[20:21] op_sel_hi:[1,0,1]
	v_pk_fma_f32 v[6:7], v[32:33], v[50:51], v[22:23] op_sel:[0,1,0]
	v_pk_fma_f32 v[8:9], v[32:33], v[52:53], v[24:25] op_sel_hi:[1,0,1]
	v_pk_fma_f32 v[10:11], v[32:33], v[52:53], v[26:27] op_sel:[0,1,0]
	v_pk_fma_f32 v[12:13], v[32:33], v[54:55], v[28:29] op_sel_hi:[1,0,1]
	v_pk_fma_f32 v[14:15], v[32:33], v[54:55], v[30:31] op_sel:[0,1,0]
	s_waitcnt lgkmcnt(0)
	v_pk_mul_f32 v[32:33], v[0:1], v[74:75] op_sel_hi:[1,0]
	v_pk_mul_f32 v[36:37], v[0:1], v[64:65] op_sel_hi:[1,0]
	v_pk_mul_f32 v[34:35], v[2:3], v[74:75] op_sel:[0,1]
	v_pk_mul_f32 v[38:39], v[2:3], v[64:65] op_sel:[0,1]
	v_pk_fma_f32 v[32:33], v[4:5], v[76:77], v[32:33] op_sel_hi:[1,0,1]
	v_pk_fma_f32 v[36:37], v[4:5], v[66:67], v[36:37] op_sel_hi:[1,0,1]
	v_pk_fma_f32 v[34:35], v[6:7], v[76:77], v[34:35] op_sel:[0,1,0]
	v_pk_fma_f32 v[38:39], v[6:7], v[66:67], v[38:39] op_sel:[0,1,0]
	v_pk_fma_f32 v[32:33], v[8:9], v[78:79], v[32:33] op_sel_hi:[1,0,1]
	v_pk_fma_f32 v[36:37], v[8:9], v[68:69], v[36:37] op_sel_hi:[1,0,1]
	v_pk_fma_f32 v[34:35], v[10:11], v[78:79], v[34:35] op_sel:[0,1,0]
	v_pk_fma_f32 v[38:39], v[10:11], v[68:69], v[38:39] op_sel:[0,1,0]
	v_pk_fma_f32 v[32:33], v[12:13], v[80:81], v[32:33] op_sel_hi:[1,0,1]
	v_pk_fma_f32 v[36:37], v[12:13], v[70:71], v[36:37] op_sel_hi:[1,0,1]
	v_pk_fma_f32 v[34:35], v[14:15], v[80:81], v[34:35] op_sel:[0,1,0]
	v_pk_fma_f32 v[38:39], v[14:15], v[70:71], v[38:39] op_sel:[0,1,0]
	v_pk_add_f32 v[36:37], v[36:37], v[38:39]
	v_pk_add_f32 v[32:33], v[32:33], v[34:35]
	ds_write2st64_b32 v134, v36, v37 offset0:0 offset1:1
	ds_read_b128 v[40:43], v132 offset:15776
	ds_read_b128 v[44:47], v132 offset:15792
	ds_read_b128 v[48:51], v132 offset:16032
	ds_read_b128 v[52:55], v132 offset:16048
	ds_read_b128 v[56:59], v132 offset:16288
	ds_read_b128 v[60:63], v132 offset:16304
	ds_read_b128 v[64:67], v132 offset:16544
	ds_read_b128 v[68:71], v132 offset:16560
	ds_read_b64 v[72:73], v133 offset:16800
	v_add_f32_dpp v32, v32, v32 row_half_mirror row_mask:0xf bank_mask:0xf bound_ctrl:1
	v_add_f32_dpp v33, v33, v33 row_half_mirror row_mask:0xf bank_mask:0xf bound_ctrl:1
	v_pk_fma_f32 v[16:17], v[106:107], v[90:91], v[0:1] op_sel_hi:[1,0,1]
	v_add_f32_dpp v32, v32, v32 quad_perm:[1,0,3,2] row_mask:0xf bank_mask:0xf bound_ctrl:1
	v_add_f32_dpp v33, v33, v33 quad_perm:[1,0,3,2] row_mask:0xf bank_mask:0xf bound_ctrl:1
	v_pk_fma_f32 v[18:19], v[106:107], v[90:91], v[2:3] op_sel:[0,1,0]
	v_add_f32_dpp v32, v32, v32 quad_perm:[2,3,0,1] row_mask:0xf bank_mask:0xf bound_ctrl:1
	v_add_f32_dpp v33, v33, v33 quad_perm:[2,3,0,1] row_mask:0xf bank_mask:0xf bound_ctrl:1
	v_pk_fma_f32 v[20:21], v[106:107], v[92:93], v[4:5] op_sel_hi:[1,0,1]
	v_pk_fma_f32 v[22:23], v[106:107], v[92:93], v[6:7] op_sel:[0,1,0]
	v_pk_fma_f32 v[24:25], v[106:107], v[94:95], v[8:9] op_sel_hi:[1,0,1]
	v_pk_fma_f32 v[26:27], v[106:107], v[94:95], v[10:11] op_sel:[0,1,0]
	v_pk_fma_f32 v[28:29], v[106:107], v[96:97], v[12:13] op_sel_hi:[1,0,1]
	v_pk_fma_f32 v[30:31], v[106:107], v[96:97], v[14:15] op_sel:[0,1,0]
	v_pk_fma_f32 v[0:1], v[32:33], v[82:83], v[16:17] op_sel_hi:[1,0,1]
	v_pk_fma_f32 v[2:3], v[32:33], v[82:83], v[18:19] op_sel:[0,1,0]
	v_pk_fma_f32 v[4:5], v[32:33], v[84:85], v[20:21] op_sel_hi:[1,0,1]
	v_pk_fma_f32 v[6:7], v[32:33], v[84:85], v[22:23] op_sel:[0,1,0]
	v_pk_fma_f32 v[8:9], v[32:33], v[86:87], v[24:25] op_sel_hi:[1,0,1]
	v_pk_fma_f32 v[10:11], v[32:33], v[86:87], v[26:27] op_sel:[0,1,0]
	v_pk_fma_f32 v[12:13], v[32:33], v[88:89], v[28:29] op_sel_hi:[1,0,1]
	v_pk_fma_f32 v[14:15], v[32:33], v[88:89], v[30:31] op_sel:[0,1,0]
	s_waitcnt lgkmcnt(0)
	v_pk_mul_f32 v[32:33], v[0:1], v[40:41] op_sel_hi:[1,0]
	v_pk_mul_f32 v[36:37], v[0:1], v[98:99] op_sel_hi:[1,0]
	v_pk_mul_f32 v[34:35], v[2:3], v[40:41] op_sel:[0,1]
	v_pk_mul_f32 v[38:39], v[2:3], v[98:99] op_sel:[0,1]
	v_pk_fma_f32 v[32:33], v[4:5], v[42:43], v[32:33] op_sel_hi:[1,0,1]
	v_pk_fma_f32 v[36:37], v[4:5], v[100:101], v[36:37] op_sel_hi:[1,0,1]
	v_pk_fma_f32 v[34:35], v[6:7], v[42:43], v[34:35] op_sel:[0,1,0]
	v_pk_fma_f32 v[38:39], v[6:7], v[100:101], v[38:39] op_sel:[0,1,0]
	v_pk_fma_f32 v[32:33], v[8:9], v[44:45], v[32:33] op_sel_hi:[1,0,1]
	v_pk_fma_f32 v[36:37], v[8:9], v[102:103], v[36:37] op_sel_hi:[1,0,1]
	v_pk_fma_f32 v[34:35], v[10:11], v[44:45], v[34:35] op_sel:[0,1,0]
	v_pk_fma_f32 v[38:39], v[10:11], v[102:103], v[38:39] op_sel:[0,1,0]
	v_pk_fma_f32 v[32:33], v[12:13], v[46:47], v[32:33] op_sel_hi:[1,0,1]
	v_pk_fma_f32 v[36:37], v[12:13], v[104:105], v[36:37] op_sel_hi:[1,0,1]
	v_pk_fma_f32 v[34:35], v[14:15], v[46:47], v[34:35] op_sel:[0,1,0]
	v_pk_fma_f32 v[38:39], v[14:15], v[104:105], v[38:39] op_sel:[0,1,0]
	v_pk_add_f32 v[36:37], v[36:37], v[38:39]
	v_pk_add_f32 v[32:33], v[32:33], v[34:35]
	ds_write2st64_b32 v134, v36, v37 offset0:2 offset1:3
	ds_read_b128 v[74:77], v132 offset:17328
	ds_read_b128 v[78:81], v132 offset:17344
	ds_read_b128 v[82:85], v132 offset:17584
	ds_read_b128 v[86:89], v132 offset:17600
	ds_read_b128 v[90:93], v132 offset:17840
	ds_read_b128 v[94:97], v132 offset:17856
	ds_read_b128 v[98:101], v132 offset:18096
	ds_read_b128 v[102:105], v132 offset:18112
	ds_read_b64 v[106:107], v133 offset:18352
	v_add_f32_dpp v32, v32, v32 row_half_mirror row_mask:0xf bank_mask:0xf bound_ctrl:1
	v_add_f32_dpp v33, v33, v33 row_half_mirror row_mask:0xf bank_mask:0xf bound_ctrl:1
	v_pk_fma_f32 v[16:17], v[72:73], v[56:57], v[0:1] op_sel_hi:[1,0,1]
	v_add_f32_dpp v32, v32, v32 quad_perm:[1,0,3,2] row_mask:0xf bank_mask:0xf bound_ctrl:1
	v_add_f32_dpp v33, v33, v33 quad_perm:[1,0,3,2] row_mask:0xf bank_mask:0xf bound_ctrl:1
	v_pk_fma_f32 v[18:19], v[72:73], v[56:57], v[2:3] op_sel:[0,1,0]
	v_add_f32_dpp v32, v32, v32 quad_perm:[2,3,0,1] row_mask:0xf bank_mask:0xf bound_ctrl:1
	v_add_f32_dpp v33, v33, v33 quad_perm:[2,3,0,1] row_mask:0xf bank_mask:0xf bound_ctrl:1
	v_pk_fma_f32 v[20:21], v[72:73], v[58:59], v[4:5] op_sel_hi:[1,0,1]
	v_pk_fma_f32 v[22:23], v[72:73], v[58:59], v[6:7] op_sel:[0,1,0]
	v_pk_fma_f32 v[24:25], v[72:73], v[60:61], v[8:9] op_sel_hi:[1,0,1]
	v_pk_fma_f32 v[26:27], v[72:73], v[60:61], v[10:11] op_sel:[0,1,0]
	v_pk_fma_f32 v[28:29], v[72:73], v[62:63], v[12:13] op_sel_hi:[1,0,1]
	v_pk_fma_f32 v[30:31], v[72:73], v[62:63], v[14:15] op_sel:[0,1,0]
	v_pk_fma_f32 v[0:1], v[32:33], v[48:49], v[16:17] op_sel_hi:[1,0,1]
	v_pk_fma_f32 v[2:3], v[32:33], v[48:49], v[18:19] op_sel:[0,1,0]
	v_pk_fma_f32 v[4:5], v[32:33], v[50:51], v[20:21] op_sel_hi:[1,0,1]
	v_pk_fma_f32 v[6:7], v[32:33], v[50:51], v[22:23] op_sel:[0,1,0]
	v_pk_fma_f32 v[8:9], v[32:33], v[52:53], v[24:25] op_sel_hi:[1,0,1]
	v_pk_fma_f32 v[10:11], v[32:33], v[52:53], v[26:27] op_sel:[0,1,0]
	v_pk_fma_f32 v[12:13], v[32:33], v[54:55], v[28:29] op_sel_hi:[1,0,1]
	v_pk_fma_f32 v[14:15], v[32:33], v[54:55], v[30:31] op_sel:[0,1,0]
	s_waitcnt lgkmcnt(0)
	v_pk_mul_f32 v[32:33], v[0:1], v[74:75] op_sel_hi:[1,0]
	v_pk_mul_f32 v[36:37], v[0:1], v[64:65] op_sel_hi:[1,0]
	v_pk_mul_f32 v[34:35], v[2:3], v[74:75] op_sel:[0,1]
	v_pk_mul_f32 v[38:39], v[2:3], v[64:65] op_sel:[0,1]
	v_pk_fma_f32 v[32:33], v[4:5], v[76:77], v[32:33] op_sel_hi:[1,0,1]
	v_pk_fma_f32 v[36:37], v[4:5], v[66:67], v[36:37] op_sel_hi:[1,0,1]
	v_pk_fma_f32 v[34:35], v[6:7], v[76:77], v[34:35] op_sel:[0,1,0]
	v_pk_fma_f32 v[38:39], v[6:7], v[66:67], v[38:39] op_sel:[0,1,0]
	v_pk_fma_f32 v[32:33], v[8:9], v[78:79], v[32:33] op_sel_hi:[1,0,1]
	v_pk_fma_f32 v[36:37], v[8:9], v[68:69], v[36:37] op_sel_hi:[1,0,1]
	v_pk_fma_f32 v[34:35], v[10:11], v[78:79], v[34:35] op_sel:[0,1,0]
	v_pk_fma_f32 v[38:39], v[10:11], v[68:69], v[38:39] op_sel:[0,1,0]
	v_pk_fma_f32 v[32:33], v[12:13], v[80:81], v[32:33] op_sel_hi:[1,0,1]
	v_pk_fma_f32 v[36:37], v[12:13], v[70:71], v[36:37] op_sel_hi:[1,0,1]
	v_pk_fma_f32 v[34:35], v[14:15], v[80:81], v[34:35] op_sel:[0,1,0]
	v_pk_fma_f32 v[38:39], v[14:15], v[70:71], v[38:39] op_sel:[0,1,0]
	v_pk_add_f32 v[36:37], v[36:37], v[38:39]
	v_pk_add_f32 v[32:33], v[32:33], v[34:35]
	ds_write2st64_b32 v134, v36, v37 offset0:4 offset1:5
	ds_read_b128 v[40:43], v132 offset:18880
	ds_read_b128 v[44:47], v132 offset:18896
	ds_read_b128 v[48:51], v132 offset:19136
	ds_read_b128 v[52:55], v132 offset:19152
	ds_read_b128 v[56:59], v132 offset:19392
	ds_read_b128 v[60:63], v132 offset:19408
	ds_read_b128 v[64:67], v132 offset:19648
	ds_read_b128 v[68:71], v132 offset:19664
	ds_read_b64 v[72:73], v133 offset:19904
	v_add_f32_dpp v32, v32, v32 row_half_mirror row_mask:0xf bank_mask:0xf bound_ctrl:1
	v_add_f32_dpp v33, v33, v33 row_half_mirror row_mask:0xf bank_mask:0xf bound_ctrl:1
	v_pk_fma_f32 v[16:17], v[106:107], v[90:91], v[0:1] op_sel_hi:[1,0,1]
	v_add_f32_dpp v32, v32, v32 quad_perm:[1,0,3,2] row_mask:0xf bank_mask:0xf bound_ctrl:1
	v_add_f32_dpp v33, v33, v33 quad_perm:[1,0,3,2] row_mask:0xf bank_mask:0xf bound_ctrl:1
	v_pk_fma_f32 v[18:19], v[106:107], v[90:91], v[2:3] op_sel:[0,1,0]
	v_add_f32_dpp v32, v32, v32 quad_perm:[2,3,0,1] row_mask:0xf bank_mask:0xf bound_ctrl:1
	v_add_f32_dpp v33, v33, v33 quad_perm:[2,3,0,1] row_mask:0xf bank_mask:0xf bound_ctrl:1
	v_pk_fma_f32 v[20:21], v[106:107], v[92:93], v[4:5] op_sel_hi:[1,0,1]
	v_pk_fma_f32 v[22:23], v[106:107], v[92:93], v[6:7] op_sel:[0,1,0]
	v_pk_fma_f32 v[24:25], v[106:107], v[94:95], v[8:9] op_sel_hi:[1,0,1]
	v_pk_fma_f32 v[26:27], v[106:107], v[94:95], v[10:11] op_sel:[0,1,0]
	v_pk_fma_f32 v[28:29], v[106:107], v[96:97], v[12:13] op_sel_hi:[1,0,1]
	v_pk_fma_f32 v[30:31], v[106:107], v[96:97], v[14:15] op_sel:[0,1,0]
	v_pk_fma_f32 v[0:1], v[32:33], v[82:83], v[16:17] op_sel_hi:[1,0,1]
	v_pk_fma_f32 v[2:3], v[32:33], v[82:83], v[18:19] op_sel:[0,1,0]
	v_pk_fma_f32 v[4:5], v[32:33], v[84:85], v[20:21] op_sel_hi:[1,0,1]
	v_pk_fma_f32 v[6:7], v[32:33], v[84:85], v[22:23] op_sel:[0,1,0]
	v_pk_fma_f32 v[8:9], v[32:33], v[86:87], v[24:25] op_sel_hi:[1,0,1]
	v_pk_fma_f32 v[10:11], v[32:33], v[86:87], v[26:27] op_sel:[0,1,0]
	v_pk_fma_f32 v[12:13], v[32:33], v[88:89], v[28:29] op_sel_hi:[1,0,1]
	v_pk_fma_f32 v[14:15], v[32:33], v[88:89], v[30:31] op_sel:[0,1,0]
	s_waitcnt lgkmcnt(0)
	v_pk_mul_f32 v[32:33], v[0:1], v[40:41] op_sel_hi:[1,0]
	v_pk_mul_f32 v[36:37], v[0:1], v[98:99] op_sel_hi:[1,0]
	v_pk_mul_f32 v[34:35], v[2:3], v[40:41] op_sel:[0,1]
	v_pk_mul_f32 v[38:39], v[2:3], v[98:99] op_sel:[0,1]
	v_pk_fma_f32 v[32:33], v[4:5], v[42:43], v[32:33] op_sel_hi:[1,0,1]
	v_pk_fma_f32 v[36:37], v[4:5], v[100:101], v[36:37] op_sel_hi:[1,0,1]
	v_pk_fma_f32 v[34:35], v[6:7], v[42:43], v[34:35] op_sel:[0,1,0]
	v_pk_fma_f32 v[38:39], v[6:7], v[100:101], v[38:39] op_sel:[0,1,0]
	v_pk_fma_f32 v[32:33], v[8:9], v[44:45], v[32:33] op_sel_hi:[1,0,1]
	v_pk_fma_f32 v[36:37], v[8:9], v[102:103], v[36:37] op_sel_hi:[1,0,1]
	v_pk_fma_f32 v[34:35], v[10:11], v[44:45], v[34:35] op_sel:[0,1,0]
	v_pk_fma_f32 v[38:39], v[10:11], v[102:103], v[38:39] op_sel:[0,1,0]
	v_pk_fma_f32 v[32:33], v[12:13], v[46:47], v[32:33] op_sel_hi:[1,0,1]
	v_pk_fma_f32 v[36:37], v[12:13], v[104:105], v[36:37] op_sel_hi:[1,0,1]
	v_pk_fma_f32 v[34:35], v[14:15], v[46:47], v[34:35] op_sel:[0,1,0]
	v_pk_fma_f32 v[38:39], v[14:15], v[104:105], v[38:39] op_sel:[0,1,0]
	v_pk_add_f32 v[36:37], v[36:37], v[38:39]
	v_pk_add_f32 v[32:33], v[32:33], v[34:35]
	ds_write2st64_b32 v134, v36, v37 offset0:6 offset1:7
	ds_read_b128 v[74:77], v132 offset:20432
	ds_read_b128 v[78:81], v132 offset:20448
	ds_read_b128 v[82:85], v132 offset:20688
	ds_read_b128 v[86:89], v132 offset:20704
	ds_read_b128 v[90:93], v132 offset:20944
	ds_read_b128 v[94:97], v132 offset:20960
	ds_read_b128 v[98:101], v132 offset:21200
	ds_read_b128 v[102:105], v132 offset:21216
	ds_read_b64 v[106:107], v133 offset:21456
	v_add_f32_dpp v32, v32, v32 row_half_mirror row_mask:0xf bank_mask:0xf bound_ctrl:1
	v_add_f32_dpp v33, v33, v33 row_half_mirror row_mask:0xf bank_mask:0xf bound_ctrl:1
	v_pk_fma_f32 v[16:17], v[72:73], v[56:57], v[0:1] op_sel_hi:[1,0,1]
	v_add_f32_dpp v32, v32, v32 quad_perm:[1,0,3,2] row_mask:0xf bank_mask:0xf bound_ctrl:1
	v_add_f32_dpp v33, v33, v33 quad_perm:[1,0,3,2] row_mask:0xf bank_mask:0xf bound_ctrl:1
	v_pk_fma_f32 v[18:19], v[72:73], v[56:57], v[2:3] op_sel:[0,1,0]
	v_add_f32_dpp v32, v32, v32 quad_perm:[2,3,0,1] row_mask:0xf bank_mask:0xf bound_ctrl:1
	v_add_f32_dpp v33, v33, v33 quad_perm:[2,3,0,1] row_mask:0xf bank_mask:0xf bound_ctrl:1
	v_pk_fma_f32 v[20:21], v[72:73], v[58:59], v[4:5] op_sel_hi:[1,0,1]
	v_pk_fma_f32 v[22:23], v[72:73], v[58:59], v[6:7] op_sel:[0,1,0]
	v_pk_fma_f32 v[24:25], v[72:73], v[60:61], v[8:9] op_sel_hi:[1,0,1]
	v_pk_fma_f32 v[26:27], v[72:73], v[60:61], v[10:11] op_sel:[0,1,0]
	v_pk_fma_f32 v[28:29], v[72:73], v[62:63], v[12:13] op_sel_hi:[1,0,1]
	v_pk_fma_f32 v[30:31], v[72:73], v[62:63], v[14:15] op_sel:[0,1,0]
	v_pk_fma_f32 v[0:1], v[32:33], v[48:49], v[16:17] op_sel_hi:[1,0,1]
	v_pk_fma_f32 v[2:3], v[32:33], v[48:49], v[18:19] op_sel:[0,1,0]
	v_pk_fma_f32 v[4:5], v[32:33], v[50:51], v[20:21] op_sel_hi:[1,0,1]
	v_pk_fma_f32 v[6:7], v[32:33], v[50:51], v[22:23] op_sel:[0,1,0]
	v_pk_fma_f32 v[8:9], v[32:33], v[52:53], v[24:25] op_sel_hi:[1,0,1]
	v_pk_fma_f32 v[10:11], v[32:33], v[52:53], v[26:27] op_sel:[0,1,0]
	v_pk_fma_f32 v[12:13], v[32:33], v[54:55], v[28:29] op_sel_hi:[1,0,1]
	v_pk_fma_f32 v[14:15], v[32:33], v[54:55], v[30:31] op_sel:[0,1,0]
	s_waitcnt lgkmcnt(0)
	v_pk_mul_f32 v[32:33], v[0:1], v[74:75] op_sel_hi:[1,0]
	v_pk_mul_f32 v[36:37], v[0:1], v[64:65] op_sel_hi:[1,0]
	v_pk_mul_f32 v[34:35], v[2:3], v[74:75] op_sel:[0,1]
	v_pk_mul_f32 v[38:39], v[2:3], v[64:65] op_sel:[0,1]
	v_pk_fma_f32 v[32:33], v[4:5], v[76:77], v[32:33] op_sel_hi:[1,0,1]
	v_pk_fma_f32 v[36:37], v[4:5], v[66:67], v[36:37] op_sel_hi:[1,0,1]
	v_pk_fma_f32 v[34:35], v[6:7], v[76:77], v[34:35] op_sel:[0,1,0]
	v_pk_fma_f32 v[38:39], v[6:7], v[66:67], v[38:39] op_sel:[0,1,0]
	v_pk_fma_f32 v[32:33], v[8:9], v[78:79], v[32:33] op_sel_hi:[1,0,1]
	v_pk_fma_f32 v[36:37], v[8:9], v[68:69], v[36:37] op_sel_hi:[1,0,1]
	v_pk_fma_f32 v[34:35], v[10:11], v[78:79], v[34:35] op_sel:[0,1,0]
	v_pk_fma_f32 v[38:39], v[10:11], v[68:69], v[38:39] op_sel:[0,1,0]
	v_pk_fma_f32 v[32:33], v[12:13], v[80:81], v[32:33] op_sel_hi:[1,0,1]
	v_pk_fma_f32 v[36:37], v[12:13], v[70:71], v[36:37] op_sel_hi:[1,0,1]
	v_pk_fma_f32 v[34:35], v[14:15], v[80:81], v[34:35] op_sel:[0,1,0]
	v_pk_fma_f32 v[38:39], v[14:15], v[70:71], v[38:39] op_sel:[0,1,0]
	v_pk_add_f32 v[36:37], v[36:37], v[38:39]
	v_pk_add_f32 v[32:33], v[32:33], v[34:35]
	ds_write2st64_b32 v134, v36, v37 offset0:8 offset1:9
	ds_read_b128 v[40:43], v132 offset:21984
	ds_read_b128 v[44:47], v132 offset:22000
	ds_read_b128 v[48:51], v132 offset:22240
	ds_read_b128 v[52:55], v132 offset:22256
	ds_read_b128 v[56:59], v132 offset:22496
	ds_read_b128 v[60:63], v132 offset:22512
	ds_read_b128 v[64:67], v132 offset:22752
	ds_read_b128 v[68:71], v132 offset:22768
	ds_read_b64 v[72:73], v133 offset:23008
	v_add_f32_dpp v32, v32, v32 row_half_mirror row_mask:0xf bank_mask:0xf bound_ctrl:1
	v_add_f32_dpp v33, v33, v33 row_half_mirror row_mask:0xf bank_mask:0xf bound_ctrl:1
	v_pk_fma_f32 v[16:17], v[106:107], v[90:91], v[0:1] op_sel_hi:[1,0,1]
	v_add_f32_dpp v32, v32, v32 quad_perm:[1,0,3,2] row_mask:0xf bank_mask:0xf bound_ctrl:1
	v_add_f32_dpp v33, v33, v33 quad_perm:[1,0,3,2] row_mask:0xf bank_mask:0xf bound_ctrl:1
	v_pk_fma_f32 v[18:19], v[106:107], v[90:91], v[2:3] op_sel:[0,1,0]
	v_add_f32_dpp v32, v32, v32 quad_perm:[2,3,0,1] row_mask:0xf bank_mask:0xf bound_ctrl:1
	v_add_f32_dpp v33, v33, v33 quad_perm:[2,3,0,1] row_mask:0xf bank_mask:0xf bound_ctrl:1
	v_pk_fma_f32 v[20:21], v[106:107], v[92:93], v[4:5] op_sel_hi:[1,0,1]
	v_pk_fma_f32 v[22:23], v[106:107], v[92:93], v[6:7] op_sel:[0,1,0]
	v_pk_fma_f32 v[24:25], v[106:107], v[94:95], v[8:9] op_sel_hi:[1,0,1]
	v_pk_fma_f32 v[26:27], v[106:107], v[94:95], v[10:11] op_sel:[0,1,0]
	v_pk_fma_f32 v[28:29], v[106:107], v[96:97], v[12:13] op_sel_hi:[1,0,1]
	v_pk_fma_f32 v[30:31], v[106:107], v[96:97], v[14:15] op_sel:[0,1,0]
	v_pk_fma_f32 v[0:1], v[32:33], v[82:83], v[16:17] op_sel_hi:[1,0,1]
	v_pk_fma_f32 v[2:3], v[32:33], v[82:83], v[18:19] op_sel:[0,1,0]
	v_pk_fma_f32 v[4:5], v[32:33], v[84:85], v[20:21] op_sel_hi:[1,0,1]
	v_pk_fma_f32 v[6:7], v[32:33], v[84:85], v[22:23] op_sel:[0,1,0]
	v_pk_fma_f32 v[8:9], v[32:33], v[86:87], v[24:25] op_sel_hi:[1,0,1]
	v_pk_fma_f32 v[10:11], v[32:33], v[86:87], v[26:27] op_sel:[0,1,0]
	v_pk_fma_f32 v[12:13], v[32:33], v[88:89], v[28:29] op_sel_hi:[1,0,1]
	v_pk_fma_f32 v[14:15], v[32:33], v[88:89], v[30:31] op_sel:[0,1,0]
	s_waitcnt lgkmcnt(0)
	v_pk_mul_f32 v[32:33], v[0:1], v[40:41] op_sel_hi:[1,0]
	v_pk_mul_f32 v[36:37], v[0:1], v[98:99] op_sel_hi:[1,0]
	v_pk_mul_f32 v[34:35], v[2:3], v[40:41] op_sel:[0,1]
	v_pk_mul_f32 v[38:39], v[2:3], v[98:99] op_sel:[0,1]
	v_pk_fma_f32 v[32:33], v[4:5], v[42:43], v[32:33] op_sel_hi:[1,0,1]
	v_pk_fma_f32 v[36:37], v[4:5], v[100:101], v[36:37] op_sel_hi:[1,0,1]
	v_pk_fma_f32 v[34:35], v[6:7], v[42:43], v[34:35] op_sel:[0,1,0]
	v_pk_fma_f32 v[38:39], v[6:7], v[100:101], v[38:39] op_sel:[0,1,0]
	v_pk_fma_f32 v[32:33], v[8:9], v[44:45], v[32:33] op_sel_hi:[1,0,1]
	v_pk_fma_f32 v[36:37], v[8:9], v[102:103], v[36:37] op_sel_hi:[1,0,1]
	v_pk_fma_f32 v[34:35], v[10:11], v[44:45], v[34:35] op_sel:[0,1,0]
	v_pk_fma_f32 v[38:39], v[10:11], v[102:103], v[38:39] op_sel:[0,1,0]
	v_pk_fma_f32 v[32:33], v[12:13], v[46:47], v[32:33] op_sel_hi:[1,0,1]
	v_pk_fma_f32 v[36:37], v[12:13], v[104:105], v[36:37] op_sel_hi:[1,0,1]
	v_pk_fma_f32 v[34:35], v[14:15], v[46:47], v[34:35] op_sel:[0,1,0]
	v_pk_fma_f32 v[38:39], v[14:15], v[104:105], v[38:39] op_sel:[0,1,0]
	v_pk_add_f32 v[36:37], v[36:37], v[38:39]
	v_pk_add_f32 v[32:33], v[32:33], v[34:35]
	ds_write2st64_b32 v134, v36, v37 offset0:10 offset1:11
	ds_read_b128 v[74:77], v132 offset:23536
	ds_read_b128 v[78:81], v132 offset:23552
	ds_read_b128 v[82:85], v132 offset:23792
	ds_read_b128 v[86:89], v132 offset:23808
	ds_read_b128 v[90:93], v132 offset:24048
	ds_read_b128 v[94:97], v132 offset:24064
	ds_read_b128 v[98:101], v132 offset:24304
	ds_read_b128 v[102:105], v132 offset:24320
	ds_read_b64 v[106:107], v133 offset:24560
	v_add_f32_dpp v32, v32, v32 row_half_mirror row_mask:0xf bank_mask:0xf bound_ctrl:1
	v_add_f32_dpp v33, v33, v33 row_half_mirror row_mask:0xf bank_mask:0xf bound_ctrl:1
	v_pk_fma_f32 v[16:17], v[72:73], v[56:57], v[0:1] op_sel_hi:[1,0,1]
	v_add_f32_dpp v32, v32, v32 quad_perm:[1,0,3,2] row_mask:0xf bank_mask:0xf bound_ctrl:1
	v_add_f32_dpp v33, v33, v33 quad_perm:[1,0,3,2] row_mask:0xf bank_mask:0xf bound_ctrl:1
	v_pk_fma_f32 v[18:19], v[72:73], v[56:57], v[2:3] op_sel:[0,1,0]
	v_add_f32_dpp v32, v32, v32 quad_perm:[2,3,0,1] row_mask:0xf bank_mask:0xf bound_ctrl:1
	v_add_f32_dpp v33, v33, v33 quad_perm:[2,3,0,1] row_mask:0xf bank_mask:0xf bound_ctrl:1
	v_pk_fma_f32 v[20:21], v[72:73], v[58:59], v[4:5] op_sel_hi:[1,0,1]
	v_pk_fma_f32 v[22:23], v[72:73], v[58:59], v[6:7] op_sel:[0,1,0]
	v_pk_fma_f32 v[24:25], v[72:73], v[60:61], v[8:9] op_sel_hi:[1,0,1]
	v_pk_fma_f32 v[26:27], v[72:73], v[60:61], v[10:11] op_sel:[0,1,0]
	v_pk_fma_f32 v[28:29], v[72:73], v[62:63], v[12:13] op_sel_hi:[1,0,1]
	v_pk_fma_f32 v[30:31], v[72:73], v[62:63], v[14:15] op_sel:[0,1,0]
	v_pk_fma_f32 v[0:1], v[32:33], v[48:49], v[16:17] op_sel_hi:[1,0,1]
	v_pk_fma_f32 v[2:3], v[32:33], v[48:49], v[18:19] op_sel:[0,1,0]
	v_pk_fma_f32 v[4:5], v[32:33], v[50:51], v[20:21] op_sel_hi:[1,0,1]
	v_pk_fma_f32 v[6:7], v[32:33], v[50:51], v[22:23] op_sel:[0,1,0]
	v_pk_fma_f32 v[8:9], v[32:33], v[52:53], v[24:25] op_sel_hi:[1,0,1]
	v_pk_fma_f32 v[10:11], v[32:33], v[52:53], v[26:27] op_sel:[0,1,0]
	v_pk_fma_f32 v[12:13], v[32:33], v[54:55], v[28:29] op_sel_hi:[1,0,1]
	v_pk_fma_f32 v[14:15], v[32:33], v[54:55], v[30:31] op_sel:[0,1,0]
	s_waitcnt lgkmcnt(0)
	v_pk_mul_f32 v[32:33], v[0:1], v[74:75] op_sel_hi:[1,0]
	v_pk_mul_f32 v[36:37], v[0:1], v[64:65] op_sel_hi:[1,0]
	v_pk_mul_f32 v[34:35], v[2:3], v[74:75] op_sel:[0,1]
	v_pk_mul_f32 v[38:39], v[2:3], v[64:65] op_sel:[0,1]
	v_pk_fma_f32 v[32:33], v[4:5], v[76:77], v[32:33] op_sel_hi:[1,0,1]
	v_pk_fma_f32 v[36:37], v[4:5], v[66:67], v[36:37] op_sel_hi:[1,0,1]
	v_pk_fma_f32 v[34:35], v[6:7], v[76:77], v[34:35] op_sel:[0,1,0]
	v_pk_fma_f32 v[38:39], v[6:7], v[66:67], v[38:39] op_sel:[0,1,0]
	v_pk_fma_f32 v[32:33], v[8:9], v[78:79], v[32:33] op_sel_hi:[1,0,1]
	v_pk_fma_f32 v[36:37], v[8:9], v[68:69], v[36:37] op_sel_hi:[1,0,1]
	v_pk_fma_f32 v[34:35], v[10:11], v[78:79], v[34:35] op_sel:[0,1,0]
	v_pk_fma_f32 v[38:39], v[10:11], v[68:69], v[38:39] op_sel:[0,1,0]
	v_pk_fma_f32 v[32:33], v[12:13], v[80:81], v[32:33] op_sel_hi:[1,0,1]
	v_pk_fma_f32 v[36:37], v[12:13], v[70:71], v[36:37] op_sel_hi:[1,0,1]
	v_pk_fma_f32 v[34:35], v[14:15], v[80:81], v[34:35] op_sel:[0,1,0]
	v_pk_fma_f32 v[38:39], v[14:15], v[70:71], v[38:39] op_sel:[0,1,0]
	v_pk_add_f32 v[36:37], v[36:37], v[38:39]
	v_pk_add_f32 v[32:33], v[32:33], v[34:35]
	ds_write2st64_b32 v134, v36, v37 offset0:12 offset1:13
	ds_read_b128 v[108:111], v132 offset:23280
	ds_read_b128 v[112:115], v132 offset:23296
	v_add_f32_dpp v32, v32, v32 row_half_mirror row_mask:0xf bank_mask:0xf bound_ctrl:1
	v_add_f32_dpp v33, v33, v33 row_half_mirror row_mask:0xf bank_mask:0xf bound_ctrl:1
	v_pk_fma_f32 v[16:17], v[106:107], v[90:91], v[0:1] op_sel_hi:[1,0,1]
	v_add_f32_dpp v32, v32, v32 quad_perm:[1,0,3,2] row_mask:0xf bank_mask:0xf bound_ctrl:1
	v_add_f32_dpp v33, v33, v33 quad_perm:[1,0,3,2] row_mask:0xf bank_mask:0xf bound_ctrl:1
	v_pk_fma_f32 v[18:19], v[106:107], v[90:91], v[2:3] op_sel:[0,1,0]
	v_add_f32_dpp v32, v32, v32 quad_perm:[2,3,0,1] row_mask:0xf bank_mask:0xf bound_ctrl:1
	v_add_f32_dpp v33, v33, v33 quad_perm:[2,3,0,1] row_mask:0xf bank_mask:0xf bound_ctrl:1
	v_pk_fma_f32 v[20:21], v[106:107], v[92:93], v[4:5] op_sel_hi:[1,0,1]
	v_pk_fma_f32 v[22:23], v[106:107], v[92:93], v[6:7] op_sel:[0,1,0]
	v_pk_fma_f32 v[24:25], v[106:107], v[94:95], v[8:9] op_sel_hi:[1,0,1]
	v_pk_fma_f32 v[26:27], v[106:107], v[94:95], v[10:11] op_sel:[0,1,0]
	v_pk_fma_f32 v[28:29], v[106:107], v[96:97], v[12:13] op_sel_hi:[1,0,1]
	v_pk_fma_f32 v[30:31], v[106:107], v[96:97], v[14:15] op_sel:[0,1,0]
	v_pk_fma_f32 v[0:1], v[32:33], v[82:83], v[16:17] op_sel_hi:[1,0,1]
	v_pk_fma_f32 v[2:3], v[32:33], v[82:83], v[18:19] op_sel:[0,1,0]
	v_pk_fma_f32 v[4:5], v[32:33], v[84:85], v[20:21] op_sel_hi:[1,0,1]
	v_pk_fma_f32 v[6:7], v[32:33], v[84:85], v[22:23] op_sel:[0,1,0]
	v_pk_fma_f32 v[8:9], v[32:33], v[86:87], v[24:25] op_sel_hi:[1,0,1]
	v_pk_fma_f32 v[10:11], v[32:33], v[86:87], v[26:27] op_sel:[0,1,0]
	v_pk_fma_f32 v[12:13], v[32:33], v[88:89], v[28:29] op_sel_hi:[1,0,1]
	v_pk_fma_f32 v[14:15], v[32:33], v[88:89], v[30:31] op_sel:[0,1,0]
	v_pk_mul_f32 v[36:37], v[0:1], v[98:99] op_sel_hi:[1,0]
	v_pk_mul_f32 v[38:39], v[2:3], v[98:99] op_sel:[0,1]
	v_pk_fma_f32 v[36:37], v[4:5], v[100:101], v[36:37] op_sel_hi:[1,0,1]
	v_pk_fma_f32 v[38:39], v[6:7], v[100:101], v[38:39] op_sel:[0,1,0]
	v_pk_fma_f32 v[36:37], v[8:9], v[102:103], v[36:37] op_sel_hi:[1,0,1]
	v_pk_fma_f32 v[38:39], v[10:11], v[102:103], v[38:39] op_sel:[0,1,0]
	v_pk_fma_f32 v[36:37], v[12:13], v[104:105], v[36:37] op_sel_hi:[1,0,1]
	v_pk_fma_f32 v[38:39], v[14:15], v[104:105], v[38:39] op_sel:[0,1,0]
	v_pk_add_f32 v[36:37], v[36:37], v[38:39]
	ds_write2st64_b32 v134, v36, v37 offset0:14 offset1:15
	ds_read_b128 v[116:119], v135
	ds_read_b128 v[120:123], v135 offset:16
	ds_read_b128 v[124:127], v135 offset:2048
	ds_read_b128 v[128:131], v135 offset:2064
	s_waitcnt lgkmcnt(2)
	v_pk_add_f32 v[116:117], v[116:117], v[118:119]
	v_pk_add_f32 v[120:121], v[120:121], v[122:123]
	s_waitcnt lgkmcnt(0)
	v_pk_add_f32 v[124:125], v[124:125], v[126:127]
	v_pk_add_f32 v[128:129], v[128:129], v[130:131]
	v_pk_add_f32 v[116:117], v[116:117], v[120:121]
	v_pk_add_f32 v[124:125], v[124:125], v[128:129]
	v_add_f32_e32 v116, v116, v117
	v_add_f32_e32 v124, v124, v125
	global_atomic_add_f32 v[136:137], v116, off
	global_atomic_add_f32 v[138:139], v124, off
	v_lshl_add_u64 v[136:137], v[136:137], 0, s[38:39]
	v_lshl_add_u64 v[138:139], v[138:139], 0, s[38:39]
	v_pk_mul_f32 v[0:1], v[0:1], v[108:109] op_sel_hi:[1,0]
	v_pk_mul_f32 v[2:3], v[2:3], v[108:109] op_sel:[0,1]
	v_pk_mul_f32 v[4:5], v[4:5], v[110:111] op_sel_hi:[1,0]
	v_pk_mul_f32 v[6:7], v[6:7], v[110:111] op_sel:[0,1]
	v_pk_mul_f32 v[8:9], v[8:9], v[112:113] op_sel_hi:[1,0]
	v_pk_mul_f32 v[10:11], v[10:11], v[112:113] op_sel:[0,1]
	v_pk_mul_f32 v[12:13], v[12:13], v[114:115] op_sel_hi:[1,0]
	v_pk_mul_f32 v[14:15], v[14:15], v[114:115] op_sel:[0,1]
	s_xor_b32 s75, s75, 0x6100
	s_waitcnt lgkmcnt(0)
	s_barrier
	s_add_i32 s74, s74, 1
	s_cmp_lt_u32 s74, s73
	s_cbranch_scc1 .Lst_chunk
	s_cmp_eq_u32 s70, 0
	s_cbranch_scc1 .Lst_item_next
	v_mov_b32_e32 v164, v0
	v_mov_b32_e32 v172, v1
	v_mov_b32_e32 v165, v2
	v_mov_b32_e32 v173, v3
	v_mov_b32_e32 v166, v4
	v_mov_b32_e32 v174, v5
	v_mov_b32_e32 v167, v6
	v_mov_b32_e32 v175, v7
	v_mov_b32_e32 v168, v8
	v_mov_b32_e32 v176, v9
	v_mov_b32_e32 v169, v10
	v_mov_b32_e32 v177, v11
	v_mov_b32_e32 v170, v12
	v_mov_b32_e32 v178, v13
	v_mov_b32_e32 v171, v14
	v_mov_b32_e32 v179, v15
	s_add_u32 s4, s20, 0x9000000
	s_addc_u32 s5, s21, 0
	s_add_u32 s4, s4, s40
	s_addc_u32 s5, s5, s41
	v_lshl_add_u64 v[182:183], v[184:185], 0, s[4:5]
	global_store_dwordx4 v[182:183], v[164:167], off
	global_store_dwordx4 v[182:183], v[168:171], off offset:16
	global_store_dwordx4 v[182:183], v[172:175], off offset:256
	global_store_dwordx4 v[182:183], v[176:179], off offset:272
.Lst_item_next:
	s_add_i32 s19, s19, s18
	s_cmp_lt_i32 s19, s71
	s_cbranch_scc1 .Lst_item
.Lst_seg_next:
	s_add_i32 s70, s70, 1
	s_cmp_lt_u32 s70, 2
	s_cbranch_scc1 .Lst_seg
	s_mov_b64 s[74:75], 0xc80000
	s_branch .LBB0_341
